# attention K/V staging loads issued together (one wait instead of eight); idle-WG weight conversion 10 items per wave with batched gain loads
# speedup vs baseline: 1.0061x; 1.0061x over previous
.LBB0_13:
	s_add_i32 s5, s5, s59
	v_writelane_b32 v250, s5, 24
	v_writelane_b32 v250, s14, 25
	s_andn2_b64 vcc, exec, s[0:1]
	s_mov_b64 s[0:1], 0
	v_writelane_b32 v250, s0, 26
	s_lshl_b32 s50, s14, 3
	s_nop 0
	v_writelane_b32 v250, s1, 27
	v_writelane_b32 v250, s48, 28
	s_nop 1
	v_writelane_b32 v250, s49, 29
	v_writelane_b32 v250, s84, 30
	s_nop 1
	v_writelane_b32 v250, s85, 31
	v_writelane_b32 v250, s86, 32
	v_writelane_b32 v250, s87, 33
	v_writelane_b32 v250, s88, 34
	v_writelane_b32 v250, s89, 35
	v_writelane_b32 v250, s90, 36
	v_writelane_b32 v250, s91, 37
	s_cbranch_vccnz .LBB0_127
	v_readlane_b32 s1, v250, 25
	s_abs_i32 s33, s1
	v_cvt_f32_u32_e32 v1, s33
	s_sub_i32 s2, 0, s33
	s_add_i32 s53, s1, 0x77f
	s_sub_i32 s1, 0xfffff881, s1
	v_rcp_iflag_f32_e32 v1, v1
	s_max_i32 s1, s53, s1
	s_ashr_i32 s0, s53, 31
	s_mov_b32 s3, 0
	v_mul_f32_e32 v1, 0x4f7ffffe, v1
	v_cvt_u32_f32_e32 v1, v1
	s_movk_i32 s26, 0x3800
	v_readfirstlane_b32 s4, v1
	s_mul_i32 s2, s2, s4
	s_mul_hi_u32 s2, s4, s2
	s_add_i32 s2, s4, s2
	s_mul_hi_u32 s4, s1, s2
	s_mul_i32 s4, s4, s33
	s_sub_i32 s1, s1, s4
	s_sub_i32 s4, s1, s33
	s_cmp_ge_u32 s1, s33
	s_cselect_b32 s1, s4, s1
	s_sub_i32 s4, s1, s33
	s_cmp_ge_u32 s1, s33
	s_cselect_b32 s1, s4, s1
	s_xor_b32 s1, s1, s0
	s_sub_i32 s0, s0, s1
	s_add_i32 s0, s53, s0
	s_cmpk_lt_i32 s0, 0x781
	s_cbranch_scc1 .LBB0_16
	s_mul_i32 s0, s0, 80
	s_add_i32 s1, s0, 0xfffda800
	s_sub_i32 s0, 0x29000, s0
	s_cmpk_lt_i32 s1, 0x3800
	s_cselect_b32 s26, s0, 0

.LBB0_127:
	v_writelane_b32 v250, s50, 38
	v_writelane_b32 v250, s60, 39
	s_mov_b32 s35, 0
	v_mbcnt_lo_u32_b32 v0, -1, 0
	v_writelane_b32 v250, s61, 40
	v_writelane_b32 v250, s62, 41
	v_writelane_b32 v250, s63, 42
	v_writelane_b32 v250, s64, 43
	v_writelane_b32 v250, s65, 44
	v_writelane_b32 v250, s66, 45
	v_writelane_b32 v250, s67, 46
	v_writelane_b32 v250, s68, 47
	v_writelane_b32 v250, s69, 48
	v_writelane_b32 v250, s70, 49
	v_writelane_b32 v250, s71, 50
	v_writelane_b32 v250, s72, 51
	v_writelane_b32 v250, s73, 52
	v_writelane_b32 v250, s74, 53
	v_writelane_b32 v250, s75, 54
	s_movk_i32 s72, 0x161
	v_readlane_b32 s26, v250, 26
	v_readlane_b32 s27, v250, 27
	s_xor_b64 s[0:1], s[26:27], -1
	v_writelane_b32 v250, s0, 55
	v_mov_b32_e32 v81, 0
	s_mov_b32 s58, 0x1e00000
	v_writelane_b32 v250, s1, 56
	s_add_u32 s0, s88, 0x20800000
	s_addc_u32 s1, s89, 0
	v_writelane_b32 v250, s0, 57
	v_mov_b32_e32 v234, 0x3727c5ac
	v_mov_b32_e32 v235, 1
	v_writelane_b32 v250, s1, 58
	s_add_u32 s0, s88, 0x22800000
	s_addc_u32 s1, s89, 0
	v_writelane_b32 v250, s0, 59
	v_mov_b32_e32 v236, 0x260
	v_mbcnt_hi_u32_b32 v237, -1, v0
	v_writelane_b32 v250, s1, 60
	s_add_u32 s0, s88, 0x23000000
	s_addc_u32 s1, s89, 0
	s_add_u32 s28, s88, 0x23800000
	v_writelane_b32 v250, s0, 61
	s_addc_u32 s29, s89, 0
	v_mov_b32_e32 v238, 0x100
	v_writelane_b32 v250, s1, 62
	s_add_u32 s0, s88, 0x27800000
	s_addc_u32 s1, s89, 0
	s_add_u32 s30, s88, 0x2f800000
	s_addc_u32 s31, s89, 0
	s_add_u32 s64, s88, 0x33800000
	s_addc_u32 s13, s89, 0
	v_writelane_b32 v250, s28, 63
	s_add_u32 s20, s88, 0x37800000
	s_addc_u32 s68, s89, 0
	v_writelane_b32 v251, s29, 0
	v_writelane_b32 v251, s0, 1
	v_readlane_b32 s23, v250, 25
	v_mov_b32_e32 v239, 0xff800000
	v_writelane_b32 v251, s1, 2
	s_add_u32 s0, s88, 0x280000
	s_addc_u32 s1, s89, 0
	v_writelane_b32 v251, s0, 3
	s_and_b32 s69, s52, 0xffffffc0
	v_mov_b64_e32 v[212:213], 0x200
	v_writelane_b32 v251, s1, 4
	s_add_u32 s0, s88, 0x800000
	v_writelane_b32 v251, s0, 5
	s_addc_u32 s0, s89, 0
	v_writelane_b32 v251, s0, 6
	s_and_b32 s25, s47, 0xffff
	v_readlane_b32 s0, v250, 2
	v_readlane_b32 s1, v250, 3
	s_cmpk_lt_i32 s0, 0x780
	s_mov_b32 s24, s0
	s_cselect_b64 s[0:1], -1, 0
	v_writelane_b32 v251, s0, 7
	v_mov_b64_e32 v[214:215], 0x1ff
	v_mov_b64_e32 v[216:217], 0xb00
	v_writelane_b32 v251, s1, 8
	s_ashr_i32 s0, s24, 31
	v_writelane_b32 v251, s0, 9
	s_lshr_b32 s0, s0, 29
	s_add_i32 s0, s24, s0
	s_ashr_i32 s7, s0, 3
	s_and_b32 s0, s0, -8
	s_sub_i32 s10, s24, s0
	s_ashr_i32 s0, s23, 31
	v_writelane_b32 v251, s0, 10
	s_add_i32 s0, s4, 0x100
	s_cmp_lt_u32 s52, 64
	v_writelane_b32 v251, s0, 11
	s_cselect_b64 s[0:1], -1, 0
	v_writelane_b32 v251, s0, 12
	v_mov_b64_e32 v[218:219], 0xaff
	s_mov_b32 s74, s35
	v_writelane_b32 v251, s1, 13
	s_add_u32 s0, s88, 0x4200
	s_addc_u32 s1, s89, 0
	v_writelane_b32 v251, s0, 14
	s_mov_b32 s50, 0x800000
	s_nop 0
	v_writelane_b32 v251, s1, 15
	s_add_u32 s0, s88, 0x4400
	s_addc_u32 s1, s89, 0
	v_writelane_b32 v251, s0, 16
	s_nop 1
	v_writelane_b32 v251, s1, 17
	s_add_u32 s0, s88, 0x4500
	s_addc_u32 s1, s89, 0
	v_writelane_b32 v251, s0, 18
	s_nop 1
	v_writelane_b32 v251, s1, 19
	s_add_u32 s0, s88, 0x4600
	s_addc_u32 s1, s89, 0
	v_writelane_b32 v251, s0, 20
	s_nop 1
	v_writelane_b32 v251, s1, 21
	s_add_u32 s0, s88, 0x4700
	s_addc_u32 s1, s89, 0
	v_writelane_b32 v251, s0, 22
	s_nop 1
	v_writelane_b32 v251, s1, 23
	s_add_u32 s0, s88, 0x4800
	s_addc_u32 s1, s89, 0
	v_writelane_b32 v251, s0, 24
	s_nop 1
	v_writelane_b32 v251, s1, 25
	s_add_u32 s0, s88, 0x4900
	s_addc_u32 s1, s89, 0
	v_writelane_b32 v251, s0, 26
	s_nop 1
	v_writelane_b32 v251, s1, 27
	s_add_u32 s0, s88, 0x4a00
	s_addc_u32 s1, s89, 0
	v_writelane_b32 v251, s0, 28
	s_nop 1
	v_writelane_b32 v251, s1, 29
	s_add_u32 s0, s88, 0x4b00
	s_addc_u32 s1, s89, 0
	v_writelane_b32 v251, s0, 30
	s_nop 1
	v_writelane_b32 v251, s1, 31
	s_add_u32 s0, s88, 0x4c00
	s_addc_u32 s1, s89, 0
	v_writelane_b32 v251, s0, 32
	s_nop 1
	v_writelane_b32 v251, s1, 33
	s_add_u32 s0, s88, 0x4d00
	s_addc_u32 s1, s89, 0
	v_writelane_b32 v251, s0, 34
	s_nop 1
	v_writelane_b32 v251, s1, 35
	s_add_u32 s0, s88, 0x4e00
	s_addc_u32 s1, s89, 0
	v_writelane_b32 v251, s0, 36
	s_nop 1
	v_writelane_b32 v251, s1, 37
	s_add_u32 s0, s88, 0x4f00
	s_addc_u32 s1, s89, 0
	v_writelane_b32 v251, s0, 38
	s_nop 1
	v_writelane_b32 v251, s1, 39
	s_add_u32 s0, s88, 0x5000
	s_addc_u32 s1, s89, 0
	v_writelane_b32 v251, s0, 40
	s_nop 1
	v_writelane_b32 v251, s1, 41
	s_add_u32 s0, s88, 0x5100
	s_addc_u32 s1, s89, 0
	v_writelane_b32 v251, s0, 42
	s_nop 1
	v_writelane_b32 v251, s1, 43
	s_add_u32 s0, s88, 0x5200
	s_addc_u32 s1, s89, 0
	v_writelane_b32 v251, s0, 44
	s_nop 1
	v_writelane_b32 v251, s1, 45
	s_add_u32 s0, s88, 0x5300
	s_addc_u32 s1, s89, 0
	v_writelane_b32 v251, s0, 46
	s_cmp_eq_u32 s54, 15
	s_nop 0
	v_writelane_b32 v251, s1, 47
	s_cselect_b64 s[0:1], -1, 0
	v_writelane_b32 v251, s0, 48
	s_cmp_eq_u32 s54, 14
	s_nop 0
	v_writelane_b32 v251, s1, 49
	s_cselect_b64 s[0:1], -1, 0
	v_writelane_b32 v251, s0, 50
	s_cmp_eq_u32 s54, 13
	s_nop 0
	v_writelane_b32 v251, s1, 51
	s_cselect_b64 s[0:1], -1, 0
	v_writelane_b32 v251, s0, 52
	s_cmp_eq_u32 s54, 12
	s_nop 0
	v_writelane_b32 v251, s1, 53
	s_cselect_b64 s[0:1], -1, 0
	v_writelane_b32 v251, s0, 54
	s_cmp_eq_u32 s54, 11
	s_nop 0
	v_writelane_b32 v251, s1, 55
	s_cselect_b64 s[0:1], -1, 0
	v_writelane_b32 v251, s0, 56
	s_cmp_eq_u32 s54, 10
	s_nop 0
	v_writelane_b32 v251, s1, 57
	s_cselect_b64 s[0:1], -1, 0
	v_writelane_b32 v251, s0, 58
	s_cmp_eq_u32 s54, 9
	s_nop 0
	v_writelane_b32 v251, s1, 59
	s_cselect_b64 s[0:1], -1, 0
	v_writelane_b32 v251, s0, 60
	s_cmp_eq_u32 s54, 8
	s_nop 0
	v_writelane_b32 v251, s1, 61
	s_cselect_b64 s[0:1], -1, 0
	v_writelane_b32 v251, s0, 62
	s_cmp_eq_u32 s54, 7
	s_nop 0
	v_writelane_b32 v251, s1, 63
	s_cselect_b64 s[0:1], -1, 0
	v_writelane_b32 v252, s0, 0
	s_cmp_eq_u32 s54, 6
	s_nop 0
	v_writelane_b32 v252, s1, 1
	s_cselect_b64 s[0:1], -1, 0
	v_writelane_b32 v252, s0, 2
	s_cmp_eq_u32 s54, 5
	s_nop 0
	v_writelane_b32 v252, s1, 3
	s_cselect_b64 s[0:1], -1, 0
	v_writelane_b32 v252, s0, 4
	s_cmp_eq_u32 s54, 4
	s_nop 0
	v_writelane_b32 v252, s1, 5
	s_cselect_b64 s[0:1], -1, 0
	v_writelane_b32 v252, s0, 6
	s_cmp_eq_u32 s54, 3
	s_nop 0
	v_writelane_b32 v252, s1, 7
	s_cselect_b64 s[0:1], -1, 0
	v_writelane_b32 v252, s0, 8
	s_cmp_eq_u32 s54, 2
	s_nop 0
	v_writelane_b32 v252, s1, 9
	s_cselect_b64 s[0:1], -1, 0
	v_writelane_b32 v252, s0, 10
	s_cmp_eq_u32 s54, 1
	s_nop 0
	v_writelane_b32 v252, s1, 11
	s_cselect_b64 s[0:1], -1, 0
	v_writelane_b32 v252, s0, 12
	s_cmp_eq_u32 s54, 0
	s_nop 0
	v_writelane_b32 v252, s1, 13
	s_cselect_b64 s[0:1], -1, 0
	v_writelane_b32 v252, s0, 14
	s_nop 1
	v_writelane_b32 v252, s1, 15
	s_lshl_b32 s0, s54, 8
	s_add_u32 s0, s8, s0
	s_addc_u32 s1, s9, 0
	s_add_u32 s4, s0, 0x1400
	s_addc_u32 s5, s1, 0
	v_writelane_b32 v252, s4, 16
	s_add_u32 s0, s0, 0x2400
	s_addc_u32 s1, s1, 0
	v_writelane_b32 v252, s5, 17
	v_writelane_b32 v252, s0, 18
	s_mov_b32 s54, 0x1600000
	s_nop 0
	v_writelane_b32 v252, s1, 19
	s_add_u32 s0, s88, 0x7400
	s_addc_u32 s1, s89, 0
	v_writelane_b32 v252, s0, 20
	s_nop 1
	v_writelane_b32 v252, s1, 21
	s_add_u32 s0, s88, 0x7500
	s_addc_u32 s1, s89, 0
	v_writelane_b32 v252, s0, 22
	s_and_b32 s4, s24, 7
	s_lshl_b32 s9, s59, 5
	v_writelane_b32 v252, s1, 23
	s_lshl_b32 s0, s59, 1
	s_and_b32 s8, s0, 2
	s_ashr_i32 s5, s24, 3
	s_lshl_b32 s0, s4, 6
	s_and_b32 s6, s9, 0x7fffffc0
	s_add_i32 s1, s0, s5
	v_writelane_b32 v252, s6, 24
	s_lshr_b32 s6, s52, 7
	v_writelane_b32 v252, s6, 25
	s_add_u32 s6, s88, 0x500000
	v_writelane_b32 v252, s6, 26
	s_addc_u32 s6, s89, 0
	v_writelane_b32 v252, s6, 27
	s_add_i32 s6, s1, s0
	v_writelane_b32 v252, s1, 28
	s_and_b64 s[0:1], s[26:27], exec
	v_readlane_b32 s0, v250, 4
	s_cselect_b32 s0, s6, s0
	s_cmpk_lt_i32 s0, 0x400
	s_cselect_b32 s6, s0, -1
	s_cmp_gt_i32 s6, -1
	v_writelane_b32 v252, s0, 29
	s_cselect_b64 s[0:1], -1, 0
	v_writelane_b32 v252, s0, 30
	s_lshr_b32 s34, s6, 3
	s_lshl_b64 s[14:15], s[34:35], 7
	v_writelane_b32 v252, s1, 31
	s_and_b32 s0, s9, 0x60
	v_writelane_b32 v252, s0, 32
	s_lshl_b32 s0, s0, 1
	v_writelane_b32 v252, s14, 33
	s_add_u32 s0, s28, s0
	s_addc_u32 s1, s29, 0
	v_writelane_b32 v252, s15, 34
	v_writelane_b32 v252, s0, 35
	s_nop 1
	v_writelane_b32 v252, s1, 36
	s_lshr_b32 s0, s52, 3
	s_bfe_u32 s1, s52, 0x10006
	v_writelane_b32 v252, s1, 37
	s_lshl_b32 s1, s24, 8
	s_and_b32 s36, s0, 0x1fffffe0
	s_and_b32 s1, s1, 0x700
	s_sub_i32 s38, 0x60, s36
	s_add_u32 s9, s88, s1
	s_addc_u32 s11, s89, 0
	s_add_u32 s0, s9, 0x14000
	s_addc_u32 s1, s11, 0
	v_writelane_b32 v252, s0, 38
	s_nop 1
	v_writelane_b32 v252, s1, 39
	s_ashr_i32 s0, s23, 3
	v_writelane_b32 v252, s0, 40
	s_add_u32 s0, s9, 0x20000
	s_addc_u32 s1, s11, 0
	v_writelane_b32 v252, s0, 41
	s_cmp_lg_u64 s[88:89], 0
	s_nop 0
	v_writelane_b32 v252, s1, 42
	s_cselect_b64 s[0:1], -1, 0
	v_writelane_b32 v252, s0, 43
	s_nop 1
	v_writelane_b32 v252, s1, 44
	s_add_u32 s0, s88, 0x2b800000
	v_writelane_b32 v252, s0, 45
	s_addc_u32 s0, s89, 0
	s_and_b32 s61, s31, 0xffff
	s_cmpk_lt_i32 s24, 0x200
	v_writelane_b32 v252, s0, 46
	s_cselect_b64 s[0:1], -1, 0
	v_writelane_b32 v252, s0, 47
	s_and_b32 s65, s13, 0xffff
	s_nop 0
	v_writelane_b32 v252, s1, 48
	s_add_i32 s0, s7, 32
	s_ashr_i32 s1, s0, 31
	s_lshr_b32 s1, s1, 26
	s_add_i32 s1, s0, s1
	s_andn2_b32 s1, s1, 63
	s_sub_i32 s12, s0, s1
	v_writelane_b32 v252, s13, 49
	s_lshl_b32 s13, s10, 6
	s_cmpk_lt_i32 s24, 0xb00
	s_cselect_b64 s[0:1], -1, 0
	v_writelane_b32 v252, s0, 50
	s_and_b32 s21, s68, 0xffff
	s_nop 0
	v_writelane_b32 v252, s1, 51
	s_and_b32 s0, s24, 3
	s_cmp_lg_u32 s0, 3
	s_cselect_b64 s[0:1], -1, 0
	s_add_u32 s70, s9, 0x20100
	s_addc_u32 s71, s11, 0
	s_cmp_lt_i32 s10, 0
	s_movk_i32 s11, 0xf1
	s_cselect_b32 s11, s11, 0xf0
	s_mul_i32 s9, s10, 0x41
	s_mul_i32 s11, s10, s11
	s_cselect_b32 s9, s9, s13
	s_cselect_b32 s13, s72, 0x160
	s_add_i32 s11, s11, s7
	s_mul_hi_i32 s14, s11, 0x88888889
	s_add_i32 s14, s14, s11
	s_lshr_b32 s15, s14, 31
	s_ashr_i32 s14, s14, 6
	s_add_i32 s14, s14, s15
	s_mul_i32 s15, s14, 0x78
	s_sub_i32 s11, s11, s15
	s_bfe_i32 s15, s11, 0x80000
	s_bfe_u32 s15, s15, 0x2000d
	s_add_i32 s15, s11, s15
	s_and_b32 s16, s15, 0xfc
	s_sub_i32 s11, s11, s16
	s_lshl_b32 s14, s14, 2
	s_sext_i32_i8 s11, s11
	s_add_i32 s34, s14, s11
	s_bfe_i32 s11, s15, 0x80000
	s_sext_i32_i16 s11, s11
	s_ashr_i32 s37, s11, 2
	s_lshl_b32 s11, s8, 5
	v_writelane_b32 v252, s11, 52
	s_or_b32 s11, s8, 1
	s_lshl_b32 s14, s11, 5
	v_writelane_b32 v252, s14, 53
	s_add_i32 s14, s8, 2
	s_lshl_b32 s15, s14, 5
	v_writelane_b32 v252, s15, 54
	s_add_i32 s15, s8, 3
	s_lshl_b32 s16, s15, 5
	v_writelane_b32 v252, s16, 55
	s_or_b32 s16, s8, 4
	s_lshl_b32 s17, s16, 5
	s_bitcmp1_b32 s59, 0
	v_writelane_b32 v252, s17, 56
	s_cselect_b64 s[18:19], -1, 0
	v_writelane_b32 v252, s18, 57
	s_add_i32 s17, s9, s7
	s_add_i32 s9, s9, s12
	v_writelane_b32 v252, s19, 58
	s_ashr_i32 s18, s17, 31
	s_lshr_b32 s18, s18, 27
	s_add_i32 s18, s17, s18
	s_and_b32 s19, s18, 0xffe0
	s_sub_i32 s17, s17, s19
	s_bfe_i32 s19, s17, 0x80000
	s_bfe_u32 s19, s19, 0x2000d
	s_add_i32 s19, s17, s19
	s_and_b32 s22, s19, 0xfc
	s_ashr_i32 s12, s9, 31
	s_sub_i32 s17, s17, s22
	s_ashr_i32 s18, s18, 5
	s_lshr_b32 s12, s12, 27
	s_lshl_b32 s18, s18, 2
	s_sext_i32_i8 s17, s17
	s_add_i32 s12, s9, s12
	s_add_i32 s22, s18, s17
	s_and_b32 s17, s12, 0xffe0
	s_sub_i32 s9, s9, s17
	s_bfe_i32 s17, s9, 0x80000
	s_bfe_u32 s17, s17, 0x2000d
	s_add_i32 s17, s9, s17
	s_and_b32 s18, s17, 0xfc
	s_sub_i32 s9, s9, s18
	s_ashr_i32 s12, s12, 5
	s_lshl_b32 s12, s12, 2
	s_sext_i32_i8 s9, s9
	s_add_i32 s18, s12, s9
	s_mul_i32 s9, s10, s13
	s_add_i32 s9, s9, s7
	s_mul_hi_i32 s7, s9, 0x2e8ba2e9
	s_lshr_b32 s10, s7, 31
	s_ashr_i32 s7, s7, 5
	s_add_i32 s7, s7, s10
	s_mul_i32 s10, s7, 0xb0
	s_sub_i32 s9, s9, s10
	s_bfe_u32 s10, s9, 0x2001d
	s_add_i32 s10, s9, s10
	s_and_b32 s12, s10, 0xfffc
	s_sub_i32 s9, s9, s12
	s_lshl_b32 s7, s7, 2
	s_sext_i32_i16 s9, s9
	s_add_i32 s12, s7, s9
	s_abs_i32 s9, s53
	s_mul_i32 s3, s9, s3
	s_mul_hi_u32 s2, s9, s2
	s_add_i32 s2, s2, s3
	s_mul_i32 s3, s2, s33
	s_sub_i32 s3, s9, s3
	s_lshl_b32 s9, s11, 6
	v_writelane_b32 v252, s9, 59
	s_lshl_b32 s9, s14, 6
	v_writelane_b32 v252, s9, 60
	s_lshl_b32 s9, s15, 6
	v_writelane_b32 v252, s9, 61
	s_lshl_b32 s9, s16, 6
	v_writelane_b32 v252, s9, 62
	s_lshl_b32 s9, s8, 6
	s_or_b32 s8, s8, 5
	v_writelane_b32 v252, s9, 63
	s_lshl_b32 s9, s8, 5
	v_writelane_b32 v253, s9, 0
	s_lshl_b32 s8, s8, 6
	v_writelane_b32 v253, s8, 1
	s_ashr_i32 s39, s38, 31
	s_bfe_i32 s8, s19, 0x80000
	v_writelane_b32 v253, s38, 2
	s_sext_i32_i16 s8, s8
	s_ashr_i32 s9, s8, 2
	v_writelane_b32 v253, s39, 3
	s_bfe_i32 s8, s17, 0x80000
	s_sext_i32_i16 s8, s8
	v_writelane_b32 v253, s9, 4
	s_lshl_b32 s9, s9, 20
	s_ashr_i32 s11, s8, 2
	s_sext_i32_i16 s8, s10
	s_or_b32 s10, s9, 0x80000
	v_writelane_b32 v253, s10, 5
	s_lshl_b32 s10, s22, 20
	v_writelane_b32 v253, s22, 6
	s_or_b32 s13, s10, 0x80000
	v_writelane_b32 v253, s13, 7
	s_or_b32 s13, s9, 0x4000
	v_writelane_b32 v253, s13, 8
	v_writelane_b32 v253, s10, 9
	s_bitset1_b32 s10, 14
	v_writelane_b32 v253, s10, 10
	v_writelane_b32 v253, s9, 11
	s_or_b32 s9, s9, 0x84000
	s_ashr_i32 s8, s8, 2
	v_writelane_b32 v253, s9, 12
	v_writelane_b32 v253, s8, 13
	s_lshl_b32 s8, s8, 20
	s_or_b32 s9, s8, 0x80000
	v_writelane_b32 v253, s9, 14
	s_lshl_b32 s9, s12, 20
	v_writelane_b32 v253, s12, 15
	s_or_b32 s10, s9, 0x80000
	v_writelane_b32 v253, s10, 16
	s_or_b32 s10, s8, 0x4000
	v_writelane_b32 v253, s10, 17
	v_writelane_b32 v253, s9, 18
	s_bitset1_b32 s9, 14
	v_writelane_b32 v253, s9, 19
	v_writelane_b32 v253, s8, 20
	s_or_b32 s8, s8, 0x84000
	v_writelane_b32 v253, s8, 21
	s_lshl_b32 s8, s37, 20
	v_writelane_b32 v253, s37, 22
	s_or_b32 s9, s8, 0x80000
	v_writelane_b32 v253, s9, 23
	s_lshl_b32 s9, s34, 20
	v_writelane_b32 v253, s34, 24
	s_or_b32 s10, s9, 0x80000
	v_writelane_b32 v253, s10, 25
	s_or_b32 s10, s8, 0x4000
	v_writelane_b32 v253, s10, 26
	v_writelane_b32 v253, s9, 27
	s_bitset1_b32 s9, 14
	v_writelane_b32 v253, s9, 28
	v_writelane_b32 v253, s8, 29
	s_or_b32 s8, s8, 0x84000
	v_writelane_b32 v253, s8, 30
	s_lshl_b32 s8, s11, 20
	s_or_b32 s9, s8, 0x80000
	v_writelane_b32 v253, s9, 31
	s_lshl_b32 s9, s18, 20
	s_or_b32 s10, s9, 0x80000
	v_writelane_b32 v253, s10, 32
	s_or_b32 s10, s8, 0x4000
	v_writelane_b32 v253, s10, 33
	v_writelane_b32 v253, s9, 34
	s_bitset1_b32 s9, 14
	v_writelane_b32 v253, s9, 35
	v_writelane_b32 v253, s8, 36
	s_or_b32 s8, s8, 0x84000
	v_writelane_b32 v253, s8, 37
	s_mul_i32 s8, s11, 0x2c0000
	v_writelane_b32 v253, s11, 38
	s_add_i32 s9, s8, 0x160000
	v_writelane_b32 v253, s9, 39
	s_mul_i32 s9, s18, 0x2c0000
	v_writelane_b32 v253, s18, 40
	s_add_i32 s10, s9, 0x160000
	v_writelane_b32 v253, s10, 41
	s_or_b32 s10, s8, 0x4000
	v_writelane_b32 v253, s10, 42
	v_writelane_b32 v253, s9, 43
	s_bitset1_b32 s9, 14
	v_writelane_b32 v253, s9, 44
	s_ashr_i32 s7, s53, 31
	v_writelane_b32 v253, s8, 45
	s_add_i32 s8, s8, 0x164000
	s_xor_b32 s7, s7, s56
	s_and_b64 s[0:1], s[0:1], s[26:27]
	v_writelane_b32 v253, s8, 46
	s_add_i32 s8, s2, 1
	s_sub_i32 s9, s3, s33
	s_cmp_ge_u32 s3, s33
	s_cselect_b32 s2, s8, s2
	s_cselect_b32 s3, s9, s3
	s_add_i32 s8, s2, 1
	s_cmp_ge_u32 s3, s33
	s_cselect_b32 s2, s8, s2
	s_xor_b32 s2, s2, s7
	s_sub_i32 s7, s2, s7
	s_mul_i32 s12, s7, s23
	s_sub_i32 s2, s12, s23
	s_add_i32 s10, s2, s24
	s_add_i32 s2, s12, 0xfffff880
	v_writelane_b32 v253, s10, 47
	s_cmpk_gt_i32 s12, 0x780
	v_writelane_b32 v253, s2, 48
	s_cselect_b64 s[2:3], -1, 0
	s_cmpk_gt_i32 s10, 0x77f
	s_cselect_b64 s[8:9], -1, 0
	s_cmp_lt_i32 s10, s12
	s_cselect_b64 s[10:11], -1, 0
	s_and_b64 s[8:9], s[8:9], s[10:11]
	s_and_b64 s[2:3], s[2:3], s[8:9]
	v_writelane_b32 v253, s2, 49
	s_mov_b32 s37, s35
	s_brev_b32 s26, 32
	v_writelane_b32 v253, s3, 50
	s_mul_i32 s2, s12, 0xffffffb0
	s_add_i32 s2, s2, 0x29000
	s_cmpk_lt_u32 s12, 0x834
	s_cselect_b32 s2, s2, 0
	s_add_i32 s2, s2, s59
	s_lshl_b32 s3, s6, 8
	s_and_b32 s3, s3, 0x700
	s_add_i32 s6, s2, 0xffffc400
	v_writelane_b32 v253, s59, 51
	s_add_u32 s8, s28, s3
	v_writelane_b32 v253, s6, 52
	s_addc_u32 s9, s29, 0
	v_writelane_b32 v253, s8, 53
	s_mov_b32 s59, 0x20000
	s_mov_b32 s33, s23
	v_writelane_b32 v253, s9, 54
	s_sub_u32 s8, 0, s36
	s_subb_u32 s9, 0, 0
	v_writelane_b32 v253, s8, 55
	s_add_i32 s7, s7, -1
	s_mul_i32 s3, s23, s7
	v_writelane_b32 v253, s9, 56
	s_lshl_b32 s3, s3, 3
	v_writelane_b32 v253, s30, 57
	s_add_i32 s2, s2, s3
	s_lshl_b32 s3, s24, 3
	v_writelane_b32 v253, s31, 58
	s_add_i32 s2, s2, s3
	v_writelane_b32 v253, s36, 59
	s_addk_i32 s2, 0x9700
	s_lshl_b32 s3, s4, 7
	v_writelane_b32 v253, s37, 60
	v_writelane_b32 v253, s2, 61
	s_lshl_b32 s2, s12, 3
	s_add_i32 s3, s5, s3
	s_addk_i32 s2, 0xc400
	v_writelane_b32 v253, s2, 62
	s_add_i32 s2, s3, 32
	v_writelane_b32 v253, s2, 63
	s_mov_b32 s2, 0x13000
	s_addk_i32 s2, 0x100
	v_writelane_b32 v254, s2, 0
	s_mov_b32 s2, 0x12200
	s_addk_i32 s2, 0x100
	v_writelane_b32 v254, s2, 1
	s_mov_b32 s2, 0x23d6c
	s_addk_i32 s2, 0x100
	v_writelane_b32 v254, s2, 2
	s_xor_b64 s[0:1], s[0:1], -1
	v_writelane_b32 v254, s0, 3
	s_mov_b32 s60, s30
	s_mov_b32 s24, s46
	v_writelane_b32 v254, s1, 4
	s_mov_b32 s0, 0x12000
	s_addk_i32 s0, 0x100
	v_writelane_b32 v254, s0, 5
	s_mov_b64 s[0:1], s[60:61]
	v_writelane_b32 v254, s0, 6
	s_mov_b32 s27, s59
	s_mov_b32 s22, 0xb000000
	v_writelane_b32 v254, s1, 7
	v_writelane_b32 v254, s2, 8
	v_writelane_b32 v254, s3, 9
	s_mov_b64 s[0:1], s[64:65]
	v_writelane_b32 v254, s0, 10
	s_mov_b32 s23, s59
	s_mov_b32 s62, s26
	v_writelane_b32 v254, s1, 11
	v_writelane_b32 v254, s2, 12
	v_writelane_b32 v254, s3, 13
	v_writelane_b32 v254, s68, 14
	v_writelane_b32 v254, s69, 15
	v_writelane_b32 v254, s70, 16
	s_mov_b32 s63, s59
	s_mov_b32 s66, s26
	s_mov_b32 s67, s59
	s_mov_b32 s30, 0x2c00000
	v_writelane_b32 v254, s71, 17
	s_branch .LBB0_131

.LBB0_370:
	v_readlane_b32 s0, v253, 49
	v_readlane_b32 s1, v253, 50
	s_andn2_b64 vcc, exec, s[0:1]
	s_cbranch_vccnz .LBB0_397
	s_mul_hi_u32 s1, s74, 0x2c00000
	s_mul_i32 s0, s74, 0x2c00000
	s_mov_b64 s[28:29], s[74:75]
	v_readlane_b32 s68, v250, 6
	v_readlane_b32 s82, v250, 20
	v_readlane_b32 s83, v250, 21
	s_add_u32 s0, s82, s0
	s_addc_u32 s1, s83, s1
	v_readlane_b32 s16, v254, 19
	v_readlane_b32 s17, v254, 20
	s_add_u32 s2, s16, 0x5a00000
	v_readlane_b32 s80, v250, 18
	s_addc_u32 s3, s17, 0
	s_mul_i32 s4, s28, 0x5800000
	v_readlane_b32 s81, v250, 19
	s_mul_hi_u32 s5, s28, 0x5800000
	s_add_u32 s4, s80, s4
	s_addc_u32 s5, s81, s5
	s_add_u32 s6, s16, 0x2e00000
	s_addc_u32 s7, s17, 0
	s_lshl_b32 s34, s28, 11
	v_readlane_b32 s78, v250, 16
	s_lshl_b64 s[36:37], s[34:35], 2
	v_readlane_b32 s79, v250, 17
	s_add_u32 s8, s78, s36
	v_readlane_b32 s76, v250, 14
	s_addc_u32 s9, s79, s37
	s_lshl_b64 s[10:11], s[28:29], 24
	v_readlane_b32 s77, v250, 15
	s_add_u32 s10, s76, s10
	s_addc_u32 s11, s77, s11
	s_add_u32 s12, s16, 0x2600000
	v_readlane_b32 s74, v250, 12
	s_addc_u32 s13, s17, 0
	s_lshl_b64 s[18:19], s[28:29], 23
	v_readlane_b32 s75, v250, 13
	s_add_u32 s14, s74, s18
	s_addc_u32 s15, s75, s19
	s_add_u32 s16, s16, 0x1e00000
	v_readlane_b32 s72, v250, 10
	s_addc_u32 s17, s17, 0
	v_and_b32_e32 v4, 15, v240
	v_lshlrev_b32_e32 v7, 2, v240
	v_readlane_b32 s73, v250, 11
	s_add_u32 s18, s72, s18
	v_readlane_b32 s80, v250, 39
	v_lshlrev_b32_e32 v4, 6, v4
	v_and_b32_e32 v6, 48, v240
	v_and_b32_e32 v7, 32, v7
	s_addc_u32 s19, s73, s19
	s_mul_hi_u32 s29, s28, 0x3c00000
	s_mul_i32 s28, s28, 0x3c00000
	v_readlane_b32 s86, v250, 45
	s_waitcnt lgkmcnt(0)
	v_and_b32_e32 v1, 31, v240
	v_readlane_b32 s33, v251, 11
	v_bfe_u32 v5, v240, 2, 2
	v_bitop3_b32 v64, v4, v7, v6 bitop3:0x36
	v_lshrrev_b32_e32 v4, 1, v240
	v_readlane_b32 s87, v250, 46
	s_add_u32 s28, s86, s28
	v_lshlrev_b32_e32 v0, 2, v1
	v_mov_b32_e32 v2, s33
	v_lshl_add_u32 v1, v1, 3, s33
	v_and_or_b32 v4, v4, 24, v5
	s_movk_i32 s33, 0x110
	v_readlane_b32 s84, v250, 43
	s_addc_u32 s29, s87, s29
	v_lshrrev_b32_e32 v68, 5, v241
	v_mad_u32_u24 v2, v4, s33, v2
	v_lshlrev_b32_e32 v4, 4, v241
	v_readlane_b32 s85, v250, 44
	s_add_u32 s36, s84, s36
	s_waitcnt lgkmcnt(0)
	v_mul_u32_u24_e32 v3, 0x110, v68
	v_and_b32_e32 v4, 48, v4
	v_readlane_b32 s78, v253, 52
	v_readlane_b32 s79, v253, 62
	v_readlane_b32 s76, v253, 47
	v_readlane_b32 s77, v253, 48
	s_addc_u32 s37, s85, s37
	s_mov_b32 s31, 10
	v_mov_b32_e32 v65, v81
	s_mov_b32 s33, 0
	v_lshlrev_b32_e32 v80, 2, v0
	v_add_u32_e32 v69, v1, v3
	v_add_u32_e32 v70, v2, v4
	v_readlane_b32 s51, v253, 61
	v_readlane_b32 s69, v250, 7
	v_readlane_b32 s70, v250, 8
	v_readlane_b32 s71, v250, 9
	v_readlane_b32 s81, v250, 40
	v_readlane_b32 s82, v250, 41
	v_readlane_b32 s83, v250, 42
	v_readlane_b32 s88, v250, 47
	v_readlane_b32 s89, v250, 48
	v_readlane_b32 s90, v250, 49
	v_readlane_b32 s91, v250, 50
	v_readlane_b32 s92, v250, 51
	v_readlane_b32 s93, v250, 52
	v_readlane_b32 s94, v250, 53
	v_readlane_b32 s95, v250, 54
	s_branch .LBB0_374

.LBB0_391:
	s_lshr_b32 s48, s71, 7
	v_cvt_f32_u32_e32 v0, s48
	s_sub_i32 s69, 0, s48
	s_abs_i32 s68, s34
	s_ashr_i32 s49, s34, 31
	v_rcp_iflag_f32_e32 v0, v0
	s_nop 0
	v_mul_f32_e32 v0, 0x4f7ffffe, v0
	v_cvt_u32_f32_e32 v0, v0
	s_nop 0
	v_readfirstlane_b32 s70, v0
	s_mul_i32 s69, s69, s70
	s_mul_hi_u32 s69, s70, s69
	s_add_i32 s70, s70, s69
	s_mul_hi_u32 s69, s68, s70
	s_mul_i32 s70, s69, s48
	s_sub_i32 s68, s68, s70
	s_add_i32 s72, s69, 1
	s_sub_i32 s70, s68, s48
	s_cmp_ge_u32 s68, s48
	s_cselect_b32 s69, s72, s69
	s_cselect_b32 s68, s70, s68
	s_add_i32 s70, s69, 1
	s_cmp_ge_u32 s68, s48
	s_cselect_b32 s68, s70, s69
	s_xor_b32 s68, s68, s49
	s_sub_i32 s68, s68, s49
	s_lshl_b32 s69, s68, 5
	v_or_b32_e32 v66, s69, v68
	v_mad_u64_u32 v[0:1], s[72:73], v66, s71, 0
	s_mul_i32 s48, s68, s48
	v_ashrrev_i32_e32 v67, 31, v66
	v_mov_b32_e32 v2, v1
	s_sub_i32 s70, s34, s48
	v_mad_u64_u32 v[2:3], s[72:73], v67, s71, v[2:3]
	s_lshl_b32 s48, s70, 7
	v_mov_b32_e32 v1, v2
	v_lshl_add_u64 v[0:1], v[0:1], 2, s[56:57]
	s_ashr_i32 s49, s48, 31
	v_lshl_add_u64 v[0:1], s[48:49], 2, v[0:1]
	s_waitcnt vmcnt(5)
	v_lshl_add_u64 v[48:49], v[0:1], 0, v[80:81]
	s_lshl_b32 s34, s71, 1
	v_lshl_add_u64 v[0:1], s[34:35], 2, v[48:49]
	s_lshl_b32 s34, s71, 2
	v_lshl_add_u64 v[4:5], s[34:35], 2, v[48:49]
	s_mul_i32 s34, s71, 6
	v_lshl_add_u64 v[6:7], s[34:35], 2, v[48:49]
	s_lshl_b32 s34, s71, 3
	v_lshl_add_u64 v[12:13], s[34:35], 2, v[48:49]
	s_mul_i32 s34, s71, 10
	v_lshl_add_u64 v[14:15], s[34:35], 2, v[48:49]
	s_mul_i32 s34, s71, 12
	v_lshl_add_u64 v[16:17], s[34:35], 2, v[48:49]
	s_mul_i32 s34, s71, 14
	v_lshl_add_u64 v[18:19], s[34:35], 2, v[48:49]
	s_lshl_b32 s34, s71, 4
	v_lshl_add_u64 v[24:25], s[34:35], 2, v[48:49]
	s_mul_i32 s34, s71, 18
	v_lshl_add_u64 v[26:27], s[34:35], 2, v[48:49]
	s_mul_i32 s34, s71, 20
	v_lshl_add_u64 v[32:33], s[34:35], 2, v[48:49]
	s_mul_i32 s34, s71, 22
	v_lshl_add_u64 v[34:35], s[34:35], 2, v[48:49]
	s_mul_i32 s34, s71, 24
	v_lshl_add_u64 v[40:41], s[34:35], 2, v[48:49]
	s_mul_i32 s34, s71, 26
	v_lshl_add_u64 v[42:43], s[34:35], 2, v[48:49]
	s_mul_i32 s34, s71, 28
	v_lshl_add_u64 v[50:51], s[34:35], 2, v[48:49]
	s_mul_i32 s34, s71, 30
	global_load_dwordx4 v[8:11], v[48:49], off nt
	s_nop 0
	global_load_dwordx4 v[0:3], v[0:1], off nt
	v_lshl_add_u64 v[48:49], s[34:35], 2, v[48:49]
	global_load_dwordx4 v[20:23], v[4:5], off nt
	s_nop 0
	global_load_dwordx4 v[4:7], v[6:7], off nt
	s_nop 0
	global_load_dwordx4 v[28:31], v[12:13], off nt
	s_nop 0
	global_load_dwordx4 v[12:15], v[14:15], off nt
	s_nop 0
	global_load_dwordx4 v[36:39], v[16:17], off nt
	s_nop 0
	global_load_dwordx4 v[16:19], v[18:19], off nt
	s_nop 0
	global_load_dwordx4 v[44:47], v[24:25], off nt
	s_nop 0
	global_load_dwordx4 v[24:27], v[26:27], off nt
	s_nop 0
	global_load_dwordx4 v[52:55], v[32:33], off nt
	s_nop 0
	global_load_dwordx4 v[32:35], v[34:35], off nt
	s_nop 0
	global_load_dwordx4 v[56:59], v[40:41], off nt
	s_nop 0
	global_load_dwordx4 v[40:43], v[42:43], off nt
	s_nop 0
	global_load_dwordx4 v[60:63], v[50:51], off nt
	s_nop 0
	global_load_dwordx4 v[48:51], v[48:49], off nt
	s_cmp_eq_u64 s[52:53], 0
	s_cbranch_scc1 .LBB0_393
	v_lshl_add_u64 v[66:67], v[66:67], 2, s[52:53]
	global_load_dword v73, v[66:67], off offset:120
	global_load_dword v72, v[66:67], off
	global_load_dword v74, v[66:67], off offset:8
	global_load_dword v76, v[66:67], off offset:16
	global_load_dword v78, v[66:67], off offset:24
	global_load_dword v82, v[66:67], off offset:32
	global_load_dword v84, v[66:67], off offset:40
	global_load_dword v86, v[66:67], off offset:48
	global_load_dword v88, v[66:67], off offset:56
	global_load_dword v90, v[66:67], off offset:64
	global_load_dword v92, v[66:67], off offset:72
	global_load_dword v94, v[66:67], off offset:80
	global_load_dword v96, v[66:67], off offset:88
	global_load_dword v98, v[66:67], off offset:96
	global_load_dword v100, v[66:67], off offset:104
	global_load_dword v102, v[66:67], off offset:112
	s_waitcnt vmcnt(14)
	v_pk_mul_f32 v[10:11], v[10:11], v[72:73] op_sel_hi:[1,0]
	v_pk_mul_f32 v[8:9], v[8:9], v[72:73] op_sel_hi:[1,0]
	s_waitcnt vmcnt(13)
	v_pk_mul_f32 v[2:3], v[2:3], v[74:75] op_sel_hi:[1,0]
	v_pk_mul_f32 v[0:1], v[0:1], v[74:75] op_sel_hi:[1,0]
	s_waitcnt vmcnt(12)
	v_pk_mul_f32 v[22:23], v[22:23], v[76:77] op_sel_hi:[1,0]
	v_pk_mul_f32 v[20:21], v[20:21], v[76:77] op_sel_hi:[1,0]
	s_waitcnt vmcnt(11)
	v_pk_mul_f32 v[6:7], v[6:7], v[78:79] op_sel_hi:[1,0]
	v_pk_mul_f32 v[4:5], v[4:5], v[78:79] op_sel_hi:[1,0]
	s_waitcnt vmcnt(10)
	v_pk_mul_f32 v[30:31], v[30:31], v[82:83] op_sel_hi:[1,0]
	v_pk_mul_f32 v[28:29], v[28:29], v[82:83] op_sel_hi:[1,0]
	s_waitcnt vmcnt(9)
	v_pk_mul_f32 v[14:15], v[14:15], v[84:85] op_sel_hi:[1,0]
	v_pk_mul_f32 v[12:13], v[12:13], v[84:85] op_sel_hi:[1,0]
	s_waitcnt vmcnt(8)
	v_pk_mul_f32 v[38:39], v[38:39], v[86:87] op_sel_hi:[1,0]
	v_pk_mul_f32 v[36:37], v[36:37], v[86:87] op_sel_hi:[1,0]
	s_waitcnt vmcnt(7)
	v_pk_mul_f32 v[18:19], v[18:19], v[88:89] op_sel_hi:[1,0]
	v_pk_mul_f32 v[16:17], v[16:17], v[88:89] op_sel_hi:[1,0]
	s_waitcnt vmcnt(6)
	v_pk_mul_f32 v[46:47], v[46:47], v[90:91] op_sel_hi:[1,0]
	v_pk_mul_f32 v[44:45], v[44:45], v[90:91] op_sel_hi:[1,0]
	s_waitcnt vmcnt(5)
	v_pk_mul_f32 v[26:27], v[26:27], v[92:93] op_sel_hi:[1,0]
	v_pk_mul_f32 v[24:25], v[24:25], v[92:93] op_sel_hi:[1,0]
	s_waitcnt vmcnt(4)
	v_pk_mul_f32 v[54:55], v[54:55], v[94:95] op_sel_hi:[1,0]
	v_pk_mul_f32 v[52:53], v[52:53], v[94:95] op_sel_hi:[1,0]
	s_waitcnt vmcnt(3)
	v_pk_mul_f32 v[34:35], v[34:35], v[96:97] op_sel_hi:[1,0]
	v_pk_mul_f32 v[32:33], v[32:33], v[96:97] op_sel_hi:[1,0]
	s_waitcnt vmcnt(2)
	v_pk_mul_f32 v[58:59], v[58:59], v[98:99] op_sel_hi:[1,0]
	v_pk_mul_f32 v[56:57], v[56:57], v[98:99] op_sel_hi:[1,0]
	s_waitcnt vmcnt(1)
	v_pk_mul_f32 v[42:43], v[42:43], v[100:101] op_sel_hi:[1,0]
	v_pk_mul_f32 v[40:41], v[40:41], v[100:101] op_sel_hi:[1,0]
	s_waitcnt vmcnt(0)
	v_pk_mul_f32 v[62:63], v[62:63], v[102:103] op_sel_hi:[1,0]
	v_pk_mul_f32 v[60:61], v[60:61], v[102:103] op_sel_hi:[1,0]
	s_waitcnt vmcnt(0)
	v_pk_mul_f32 v[50:51], v[50:51], v[72:73] op_sel:[0,1] op_sel_hi:[1,1]
	v_pk_mul_f32 v[48:49], v[48:49], v[72:73] op_sel:[0,1] op_sel_hi:[1,1]

.LBB0_453:
	s_or_b64 exec, exec, s[0:1]
	s_lshl_b32 s0, s6, 2
	v_readlane_b32 s1, v252, 25
	s_add_i32 s34, s0, s1
	s_lshl_b32 s0, s34, 2
	s_waitcnt vmcnt(0)
	ds_write_b128 v168, v[12:15]
	ds_write_b128 v169, v[16:19]
	ds_write_b128 v170, v[20:23]
	ds_write_b128 v171, v[24:27]
	ds_write_b16 v172, v28 offset:36864
	ds_write_b16_d16_hi v172, v28 offset:37392
	ds_write_b16 v172, v29 offset:37920
	ds_write_b16_d16_hi v172, v29 offset:38448
	ds_write_b16 v172, v30 offset:38976
	ds_write_b16_d16_hi v172, v30 offset:39504
	ds_write_b16 v172, v31 offset:40032
	ds_write_b16_d16_hi v172, v31 offset:40560
	ds_write_b16 v173, v32 offset:36864
	ds_write_b16_d16_hi v173, v32 offset:37392
	ds_write_b16 v173, v33 offset:37920
	ds_write_b16_d16_hi v173, v33 offset:38448
	ds_write_b16 v173, v34 offset:38976
	ds_write_b16_d16_hi v173, v34 offset:39504
	ds_write_b16 v173, v35 offset:40032
	ds_write_b16_d16_hi v173, v35 offset:40560
	ds_write_b16 v174, v36 offset:36864
	ds_write_b16_d16_hi v174, v36 offset:37392
	ds_write_b16 v174, v37 offset:37920
	ds_write_b16_d16_hi v174, v37 offset:38448
	ds_write_b16 v174, v38 offset:38976
	ds_write_b16_d16_hi v174, v38 offset:39504
	ds_write_b16 v174, v39 offset:40032
	ds_write_b16_d16_hi v174, v39 offset:40560
	ds_write_b16 v175, v4 offset:36864
	ds_write_b16_d16_hi v175, v4 offset:37392
	ds_write_b16 v175, v5 offset:37920
	ds_write_b16_d16_hi v175, v5 offset:38448
	ds_write_b16 v175, v6 offset:38976
	ds_write_b16_d16_hi v175, v6 offset:39504
	ds_write_b16 v175, v7 offset:40032
	ds_write_b16_d16_hi v175, v7 offset:40560
	v_mov_b32_e32 v4, s0
	v_readlane_b32 s0, v254, 25
	s_waitcnt lgkmcnt(0)
	s_barrier
	v_readlane_b32 s1, v254, 26
	v_and_b32_e32 v5, 64, v237
	v_add_u32_e32 v5, 64, v5
	v_readlane_b32 s48, v254, 41
	v_readlane_b32 s49, v254, 42
	v_readlane_b32 s56, v254, 43
	global_load_dword v188, v4, s[0:1]
	v_xor_b32_e32 v4, 32, v237
	v_cmp_lt_i32_e32 vcc, v4, v5
	s_and_b64 s[86:87], s[16:17], s[48:49]
	v_readlane_b32 s57, v254, 44
	v_cndmask_b32_e32 v4, v237, v4, vcc
	v_lshlrev_b32_e32 v189, 2, v4
	ds_read_b128 v[4:7], v176
	ds_read_b128 v[8:11], v176 offset:32
	s_waitcnt lgkmcnt(1)
	v_mfma_f32_32x32x16_bf16 v[64:79], v[4:7], v[0:3], 0
	ds_read_b128 v[4:7], v176 offset:64
	v_readlane_b32 s38, v254, 45
	s_and_b64 s[88:89], s[16:17], s[56:57]
	v_readlane_b32 s39, v254, 46
	v_readlane_b32 s2, v254, 47
	s_and_b64 s[90:91], s[16:17], s[38:39]
	v_readlane_b32 s3, v254, 48
	s_waitcnt lgkmcnt(1)
	v_mfma_f32_32x32x16_bf16 v[64:79], v[8:11], v[128:131], v[64:79]
	v_readlane_b32 s40, v254, 49
	v_readlane_b32 s52, v254, 37
	s_and_b64 s[92:93], s[16:17], s[2:3]
	v_readlane_b32 s41, v254, 50
	v_readlane_b32 s42, v254, 51
	v_readlane_b32 s53, v254, 38
	v_readlane_b32 s0, v254, 39
	s_waitcnt lgkmcnt(0)
	v_mfma_f32_32x32x16_bf16 v[64:79], v[4:7], v[124:127], v[64:79]
	ds_read_b128 v[4:7], v176 offset:96
	s_and_b64 s[94:95], s[16:17], s[40:41]
	v_readlane_b32 s43, v254, 52
	v_readlane_b32 s44, v254, 53
	s_and_b64 s[82:83], s[16:17], s[52:53]
	v_readlane_b32 s1, v254, 40
	s_and_b64 s[96:97], s[16:17], s[42:43]
	s_waitcnt lgkmcnt(0)
	v_mfma_f32_32x32x16_bf16 v[64:79], v[4:7], v[120:123], v[64:79]
	ds_read_b128 v[4:7], v177
	ds_read_b128 v[8:11], v177 offset:32
	v_readlane_b32 s45, v254, 54
	v_readlane_b32 s68, v254, 55
	s_and_b64 s[84:85], s[16:17], s[0:1]
	s_and_b64 s[28:29], s[16:17], s[44:45]
	v_readlane_b32 s69, v254, 56
	v_readlane_b32 s70, v254, 57
	s_waitcnt lgkmcnt(1)
	v_mfma_f32_32x32x16_bf16 v[48:63], v[4:7], v[0:3], 0
	ds_read_b128 v[4:7], v177 offset:64
	s_nop 0
	v_mul_f32_e32 v66, 0x3e38aa3b, v66
	v_mul_f32_e32 v64, 0x3e38aa3b, v64
	v_cndmask_b32_e64 v80, v239, v64, s[82:83]
	v_mul_f32_e32 v64, 0x3e38aa3b, v65
	v_cndmask_b32_e64 v65, v239, v64, s[84:85]
	s_and_b64 s[4:5], s[16:17], s[68:69]
	s_waitcnt lgkmcnt(1)
	v_mfma_f32_32x32x16_bf16 v[48:63], v[8:11], v[128:131], v[48:63]
	v_readlane_b32 s71, v254, 58
	v_readlane_b32 s72, v254, 59
	s_and_b64 s[6:7], s[16:17], s[70:71]
	v_readlane_b32 s73, v254, 60
	v_readlane_b32 s74, v254, 61
	s_and_b64 s[8:9], s[16:17], s[72:73]
	v_readlane_b32 s75, v254, 62
	s_waitcnt lgkmcnt(0)
	v_mfma_f32_32x32x16_bf16 v[48:63], v[4:7], v[124:127], v[48:63]
	ds_read_b128 v[4:7], v177 offset:96
	v_readlane_b32 s76, v254, 63
	s_and_b64 s[10:11], s[16:17], s[74:75]
	v_readlane_b32 s77, v255, 0
	v_readlane_b32 s78, v255, 1
	s_and_b64 s[12:13], s[16:17], s[76:77]
	v_readlane_b32 s79, v255, 2
	s_waitcnt lgkmcnt(0)
	v_mfma_f32_32x32x16_bf16 v[48:63], v[4:7], v[120:123], v[48:63]
	ds_read_b128 v[4:7], v178
	ds_read_b128 v[8:11], v178 offset:32
	v_readlane_b32 s36, v255, 3
	s_and_b64 s[14:15], s[16:17], s[78:79]
	v_readlane_b32 s37, v255, 4
	s_and_b64 s[18:19], s[16:17], s[36:37]
	v_readlane_b32 s80, v252, 57
	v_readlane_b32 s81, v252, 58
	s_waitcnt lgkmcnt(1)
	v_mfma_f32_32x32x16_bf16 v[32:47], v[4:7], v[0:3], 0
	ds_read_b128 v[4:7], v178 offset:64
	s_nop 0
	v_mul_f32_e32 v48, 0x3e38aa3b, v48
	s_waitcnt vmcnt(0)
	v_mul_f32_e32 v190, 0x3fb8aa3b, v188
	v_max3_f32 v64, v190, v80, v65
	v_readlane_b32 s0, v255, 5
	v_readlane_b32 s1, v255, 6
	s_add_i32 s31, s31, 1
	s_waitcnt lgkmcnt(1)
	v_mfma_f32_32x32x16_bf16 v[32:47], v[8:11], v[128:131], v[32:47]
	s_add_i32 s51, s51, 32
	s_waitcnt lgkmcnt(0)
	v_mfma_f32_32x32x16_bf16 v[32:47], v[4:7], v[124:127], v[32:47]
	ds_read_b128 v[4:7], v178 offset:96
	s_waitcnt lgkmcnt(0)
	v_mfma_f32_32x32x16_bf16 v[32:47], v[4:7], v[120:123], v[32:47]
	ds_read_b128 v[4:7], v179
	ds_read_b128 v[8:11], v179 offset:32
	s_waitcnt lgkmcnt(1)
	v_mfma_f32_32x32x16_bf16 v[16:31], v[4:7], v[0:3], 0
	ds_read_b128 v[4:7], v179 offset:64
	s_nop 6
	v_mul_f32_e32 v32, 0x3e38aa3b, v32
	s_waitcnt lgkmcnt(1)
	v_mfma_f32_32x32x16_bf16 v[16:31], v[8:11], v[128:131], v[16:31]
	s_waitcnt lgkmcnt(0)
	v_mfma_f32_32x32x16_bf16 v[16:31], v[4:7], v[124:127], v[16:31]
	ds_read_b128 v[4:7], v179 offset:96
	s_waitcnt lgkmcnt(0)
	v_mfma_f32_32x32x16_bf16 v[16:31], v[4:7], v[120:123], v[16:31]
	ds_read_b128 v[4:7], v180
	ds_read_b128 v[192:195], v180 offset:32
	s_waitcnt lgkmcnt(1)
	v_mfma_f32_32x32x16_bf16 v[0:15], v[4:7], v[0:3], 0
	s_nop 7
	v_mul_f32_e32 v16, 0x3e38aa3b, v16
	s_waitcnt lgkmcnt(0)
	v_mfma_f32_32x32x16_bf16 v[0:15], v[192:195], v[128:131], v[0:15]
	ds_read_b128 v[128:131], v180 offset:64
	s_waitcnt lgkmcnt(0)
	v_mfma_f32_32x32x16_bf16 v[0:15], v[128:131], v[124:127], v[0:15]
	ds_read_b128 v[124:127], v180 offset:96
	v_cndmask_b32_e64 v131, v239, v48, s[16:17]
	v_mul_f32_e32 v48, 0x3e38aa3b, v49
	v_mul_f32_e32 v49, 0x3e38aa3b, v50
	v_cndmask_b32_e64 v50, v239, v49, s[16:17]
	v_mul_f32_e32 v49, 0x3e38aa3b, v51
	v_cndmask_b32_e64 v51, v239, v49, s[16:17]
	s_waitcnt lgkmcnt(0)
	v_mfma_f32_32x32x16_bf16 v[0:15], v[124:127], v[120:123], v[0:15]
	v_cndmask_b32_e64 v120, v239, v66, s[86:87]
	v_mul_f32_e32 v66, 0x3e38aa3b, v67
	v_cndmask_b32_e64 v67, v239, v66, s[88:89]
	v_mul_f32_e32 v66, 0x3e38aa3b, v68
	v_cndmask_b32_e64 v121, v239, v66, s[90:91]
	v_mul_f32_e32 v66, 0x3e38aa3b, v69
	v_mul_f32_e32 v49, 0x3e38aa3b, v52
	v_cndmask_b32_e64 v69, v239, v66, s[92:93]
	v_mul_f32_e32 v66, 0x3e38aa3b, v70
	v_cndmask_b32_e64 v52, v239, v49, s[16:17]
	v_mul_f32_e32 v49, 0x3e38aa3b, v53
	v_cndmask_b32_e64 v70, v239, v66, s[94:95]
	v_mul_f32_e32 v66, 0x3e38aa3b, v71
	v_cndmask_b32_e64 v53, v239, v49, s[16:17]
	v_mul_f32_e32 v49, 0x3e38aa3b, v54
	v_cndmask_b32_e64 v71, v239, v66, s[96:97]
	v_mul_f32_e32 v66, 0x3e38aa3b, v72
	v_cndmask_b32_e64 v54, v239, v49, s[16:17]
	v_mul_f32_e32 v49, 0x3e38aa3b, v55
	v_cndmask_b32_e64 v72, v239, v66, s[28:29]
	v_mul_f32_e32 v66, 0x3e38aa3b, v73
	v_cndmask_b32_e64 v192, v239, v49, s[16:17]
	v_mul_f32_e32 v49, 0x3e38aa3b, v56
	v_cndmask_b32_e64 v126, v239, v66, s[4:5]
	v_mul_f32_e32 v66, 0x3e38aa3b, v74
	v_cndmask_b32_e64 v193, v239, v49, s[16:17]
	v_mul_f32_e32 v49, 0x3e38aa3b, v57
	v_max3_f32 v64, v64, v120, v67
	v_cndmask_b32_e64 v127, v239, v66, s[6:7]
	v_mul_f32_e32 v66, 0x3e38aa3b, v75
	v_cndmask_b32_e64 v194, v239, v49, s[16:17]
	v_mul_f32_e32 v49, 0x3e38aa3b, v58
	v_max3_f32 v64, v64, v121, v69
	v_cndmask_b32_e64 v75, v239, v66, s[8:9]
	v_mul_f32_e32 v66, 0x3e38aa3b, v76
	v_cndmask_b32_e64 v58, v239, v49, s[16:17]
	v_mul_f32_e32 v49, 0x3e38aa3b, v59
	v_max3_f32 v64, v64, v70, v71
	v_cndmask_b32_e64 v128, v239, v66, s[10:11]
	v_mul_f32_e32 v66, 0x3e38aa3b, v77
	v_cndmask_b32_e64 v195, v239, v49, s[16:17]
	v_mul_f32_e32 v49, 0x3e38aa3b, v60
	v_max3_f32 v64, v64, v72, v126
	v_cndmask_b32_e64 v77, v239, v66, s[12:13]
	v_mul_f32_e32 v66, 0x3e38aa3b, v78
	v_cndmask_b32_e64 v196, v239, v49, s[16:17]
	v_mul_f32_e32 v49, 0x3e38aa3b, v61
	v_max3_f32 v64, v64, v127, v75
	v_cndmask_b32_e64 v129, v239, v66, s[14:15]
	v_mul_f32_e32 v66, 0x3e38aa3b, v79
	v_cndmask_b32_e64 v197, v239, v49, s[16:17]
	v_mul_f32_e32 v49, 0x3e38aa3b, v62
	v_max3_f32 v64, v64, v128, v77
	v_cndmask_b32_e64 v130, v239, v66, s[18:19]
	v_cndmask_b32_e64 v198, v239, v49, s[16:17]
	v_mul_f32_e32 v49, 0x3e38aa3b, v63
	v_max3_f32 v64, v64, v129, v130
	v_cndmask_b32_e64 v191, v239, v48, s[16:17]
	v_cndmask_b32_e64 v199, v239, v49, s[16:17]
	s_or_b64 s[16:17], s[16:17], s[80:81]
	v_max3_f32 v48, v64, v131, v191
	v_cndmask_b32_e64 v200, v239, v32, s[16:17]
	v_mul_f32_e32 v32, 0x3e38aa3b, v33
	v_mul_f32_e32 v33, 0x3e38aa3b, v34
	v_max3_f32 v48, v48, v50, v51
	v_cndmask_b32_e64 v202, v239, v33, s[16:17]
	v_mul_f32_e32 v33, 0x3e38aa3b, v35
	v_max3_f32 v48, v48, v52, v53
	v_cndmask_b32_e64 v203, v239, v33, s[16:17]
	v_mul_f32_e32 v33, 0x3e38aa3b, v36
	v_max3_f32 v48, v48, v54, v192
	v_cndmask_b32_e64 v204, v239, v33, s[16:17]
	v_mul_f32_e32 v33, 0x3e38aa3b, v37
	v_max3_f32 v48, v48, v193, v194
	v_cndmask_b32_e64 v205, v239, v33, s[16:17]
	v_mul_f32_e32 v33, 0x3e38aa3b, v38
	v_max3_f32 v48, v48, v58, v195
	v_cndmask_b32_e64 v206, v239, v33, s[16:17]
	v_mul_f32_e32 v33, 0x3e38aa3b, v39
	v_cndmask_b32_e64 v74, v239, v16, s[16:17]
	v_mul_f32_e32 v16, 0x3e38aa3b, v17
	v_mul_f32_e32 v17, 0x3e38aa3b, v18
	v_max3_f32 v48, v48, v196, v197
	v_cndmask_b32_e64 v207, v239, v33, s[16:17]
	v_mul_f32_e32 v33, 0x3e38aa3b, v40
	v_cndmask_b32_e64 v68, v239, v17, s[16:17]
	v_mul_f32_e32 v17, 0x3e38aa3b, v19
	v_max3_f32 v48, v48, v198, v199
	v_cndmask_b32_e64 v201, v239, v32, s[16:17]
	v_cndmask_b32_e64 v208, v239, v33, s[16:17]
	v_mul_f32_e32 v33, 0x3e38aa3b, v41
	v_cndmask_b32_e64 v66, v239, v17, s[16:17]
	v_mul_f32_e32 v17, 0x3e38aa3b, v20
	v_max3_f32 v32, v48, v200, v201
	v_cndmask_b32_e64 v125, v239, v33, s[16:17]
	v_mul_f32_e32 v33, 0x3e38aa3b, v42
	v_cndmask_b32_e64 v64, v239, v17, s[16:17]
	v_mul_f32_e32 v17, 0x3e38aa3b, v21
	v_max3_f32 v32, v32, v202, v203
	v_cndmask_b32_e64 v124, v239, v33, s[16:17]
	v_mul_f32_e32 v33, 0x3e38aa3b, v43
	v_cndmask_b32_e64 v62, v239, v17, s[16:17]
	v_mul_f32_e32 v17, 0x3e38aa3b, v22
	v_max3_f32 v32, v32, v204, v205
	v_cndmask_b32_e64 v123, v239, v33, s[16:17]
	v_mul_f32_e32 v33, 0x3e38aa3b, v44
	v_cndmask_b32_e64 v60, v239, v17, s[16:17]
	v_mul_f32_e32 v17, 0x3e38aa3b, v23
	v_max3_f32 v32, v32, v206, v207
	v_cndmask_b32_e64 v122, v239, v33, s[16:17]
	v_mul_f32_e32 v33, 0x3e38aa3b, v45
	v_cndmask_b32_e64 v57, v239, v17, s[16:17]
	v_mul_f32_e32 v17, 0x3e38aa3b, v24
	v_max3_f32 v32, v32, v208, v125
	v_cndmask_b32_e64 v79, v239, v33, s[16:17]
	v_mul_f32_e32 v33, 0x3e38aa3b, v46
	v_cndmask_b32_e64 v59, v239, v17, s[16:17]
	v_mul_f32_e32 v17, 0x3e38aa3b, v25
	v_max3_f32 v32, v32, v124, v123
	v_cndmask_b32_e64 v78, v239, v33, s[16:17]
	v_mul_f32_e32 v33, 0x3e38aa3b, v47
	v_cndmask_b32_e64 v48, v239, v17, s[16:17]
	v_mul_f32_e32 v17, 0x3e38aa3b, v26
	v_max3_f32 v32, v32, v122, v79
	v_cndmask_b32_e64 v76, v239, v33, s[16:17]
	v_cndmask_b32_e64 v55, v239, v17, s[16:17]
	v_mul_f32_e32 v17, 0x3e38aa3b, v27
	v_max3_f32 v32, v32, v78, v76
	v_cndmask_b32_e64 v73, v239, v16, s[16:17]
	v_cndmask_b32_e64 v45, v239, v17, s[16:17]
	v_mul_f32_e32 v17, 0x3e38aa3b, v28
	v_mul_f32_e32 v0, 0x3e38aa3b, v0
	v_max3_f32 v16, v32, v74, v73
	v_cndmask_b32_e64 v46, v239, v17, s[16:17]
	v_mul_f32_e32 v17, 0x3e38aa3b, v29
	v_cndmask_b32_e64 v24, v0, v239, s[52:53]
	v_mul_f32_e32 v0, 0x3e38aa3b, v1
	v_mul_f32_e32 v1, 0x3e38aa3b, v2
	v_max3_f32 v16, v16, v68, v66
	v_cndmask_b32_e64 v27, v239, v17, s[16:17]
	v_mul_f32_e32 v17, 0x3e38aa3b, v30
	v_cndmask_b32_e64 v30, v1, v239, s[48:49]
	v_mul_f32_e32 v1, 0x3e38aa3b, v3
	v_max3_f32 v16, v16, v64, v62
	v_cndmask_b32_e64 v25, v1, v239, s[56:57]
	v_mul_f32_e32 v1, 0x3e38aa3b, v4
	v_max3_f32 v16, v16, v60, v57
	v_cndmask_b32_e64 v26, v1, v239, s[38:39]
	v_mul_f32_e32 v1, 0x3e38aa3b, v5
	v_max3_f32 v16, v16, v59, v48
	v_cndmask_b32_e64 v21, v1, v239, s[2:3]
	v_mul_f32_e32 v1, 0x3e38aa3b, v6
	v_max3_f32 v16, v16, v55, v45
	v_cndmask_b32_e64 v28, v239, v17, s[16:17]
	v_mul_f32_e32 v17, 0x3e38aa3b, v31
	v_cndmask_b32_e64 v22, v1, v239, s[40:41]
	v_mul_f32_e32 v1, 0x3e38aa3b, v7
	v_max3_f32 v16, v16, v46, v27
	v_cndmask_b32_e64 v23, v239, v17, s[16:17]
	v_cndmask_b32_e64 v19, v1, v239, s[42:43]
	v_mul_f32_e32 v1, 0x3e38aa3b, v8
	v_max3_f32 v16, v16, v28, v23
	v_cndmask_b32_e64 v29, v239, v0, s[0:1]
	v_cndmask_b32_e64 v20, v1, v239, s[44:45]
	v_mul_f32_e32 v1, 0x3e38aa3b, v9
	v_max3_f32 v0, v16, v24, v29
	v_cndmask_b32_e64 v17, v1, v239, s[68:69]
	v_mul_f32_e32 v1, 0x3e38aa3b, v10
	v_max3_f32 v0, v0, v30, v25
	v_cndmask_b32_e64 v18, v1, v239, s[70:71]
	v_mul_f32_e32 v1, 0x3e38aa3b, v11
	v_max3_f32 v0, v0, v26, v21
	v_cndmask_b32_e64 v16, v1, v239, s[72:73]
	v_mul_f32_e32 v1, 0x3e38aa3b, v12
	v_max3_f32 v0, v0, v22, v19
	v_cndmask_b32_e64 v12, v1, v239, s[74:75]
	v_mul_f32_e32 v1, 0x3e38aa3b, v13
	v_max3_f32 v0, v0, v20, v17
	v_cndmask_b32_e64 v10, v1, v239, s[76:77]
	v_mul_f32_e32 v1, 0x3e38aa3b, v14
	v_max3_f32 v0, v0, v18, v16
	v_cndmask_b32_e64 v11, v1, v239, s[78:79]
	v_mul_f32_e32 v1, 0x3e38aa3b, v15
	v_max3_f32 v0, v0, v12, v10
	v_cndmask_b32_e64 v9, v1, v239, s[36:37]
	v_max3_f32 v0, v0, v11, v9
	ds_bpermute_b32 v1, v189, v0
	s_mov_b32 s80, 0x3fb8aa3b
	s_waitcnt lgkmcnt(0)
	v_max_f32_e32 v1, v1, v1
	v_max_f32_e32 v8, v0, v1
	v_sub_f32_e32 v0, v80, v8
	v_exp_f32_e32 v0, v0
	v_sub_f32_e32 v1, v65, v8
	v_exp_f32_e32 v1, v1
	v_sub_f32_e32 v14, v72, v8
	v_add_f32_e32 v2, 0, v0
	v_exp_f32_e32 v32, v14
	v_add_f32_e32 v3, v2, v1
	v_sub_f32_e32 v2, v120, v8
	v_exp_f32_e32 v2, v2
	v_sub_f32_e32 v14, v126, v8
	v_exp_f32_e32 v33, v14
	v_sub_f32_e32 v14, v127, v8
	v_add_f32_e32 v4, v3, v2
	v_sub_f32_e32 v3, v67, v8
	v_exp_f32_e32 v3, v3
	v_exp_f32_e32 v34, v14
	v_sub_f32_e32 v14, v75, v8
	v_exp_f32_e32 v36, v14
	v_add_f32_e32 v5, v4, v3
	v_sub_f32_e32 v4, v121, v8
	v_exp_f32_e32 v4, v4
	v_sub_f32_e32 v14, v128, v8
	v_exp_f32_e32 v38, v14
	v_sub_f32_e32 v14, v77, v8
	v_add_f32_e32 v6, v5, v4
	v_sub_f32_e32 v5, v69, v8
	v_exp_f32_e32 v5, v5
	v_exp_f32_e32 v39, v14
	v_sub_f32_e32 v14, v129, v8
	v_exp_f32_e32 v44, v14
	v_add_f32_e32 v7, v6, v5
	v_sub_f32_e32 v6, v70, v8
	v_exp_f32_e32 v6, v6
	v_sub_f32_e32 v14, v130, v8
	v_exp_f32_e32 v49, v14
	v_sub_f32_e32 v14, v131, v8
	v_add_f32_e32 v13, v7, v6
	v_sub_f32_e32 v7, v71, v8
	v_exp_f32_e32 v7, v7
	v_exp_f32_e32 v35, v14
	v_sub_f32_e32 v14, v191, v8
	v_exp_f32_e32 v37, v14
	v_add_f32_e32 v13, v13, v7
	v_add_f32_e32 v13, v13, v32
	v_add_f32_e32 v13, v13, v33
	v_add_f32_e32 v13, v13, v34
	v_add_f32_e32 v13, v13, v36
	v_add_f32_e32 v13, v13, v38
	v_add_f32_e32 v13, v13, v39
	v_sub_f32_e32 v14, v50, v8
	v_add_f32_e32 v13, v13, v44
	v_exp_f32_e32 v40, v14
	v_sub_f32_e32 v14, v51, v8
	v_add_f32_e32 v13, v13, v49
	v_exp_f32_e32 v42, v14
	v_sub_f32_e32 v14, v52, v8
	v_add_f32_e32 v13, v13, v35
	v_exp_f32_e32 v47, v14
	v_sub_f32_e32 v14, v53, v8
	v_add_f32_e32 v13, v13, v37
	v_exp_f32_e32 v50, v14
	v_sub_f32_e32 v14, v54, v8
	v_add_f32_e32 v13, v13, v40
	v_exp_f32_e32 v56, v14
	v_sub_f32_e32 v14, v192, v8
	v_add_f32_e32 v13, v13, v42
	v_exp_f32_e32 v61, v14
	v_sub_f32_e32 v14, v193, v8
	v_add_f32_e32 v13, v13, v47
	v_exp_f32_e32 v41, v14
	v_sub_f32_e32 v14, v194, v8
	v_add_f32_e32 v13, v13, v50
	v_exp_f32_e32 v43, v14
	v_sub_f32_e32 v14, v58, v8
	v_add_f32_e32 v13, v13, v56
	v_exp_f32_e32 v51, v14
	v_sub_f32_e32 v14, v195, v8
	v_add_f32_e32 v13, v13, v61
	v_exp_f32_e32 v53, v14
	v_sub_f32_e32 v14, v196, v8
	v_add_f32_e32 v13, v13, v41
	v_exp_f32_e32 v58, v14
	v_sub_f32_e32 v14, v197, v8
	v_add_f32_e32 v13, v13, v43
	v_exp_f32_e32 v63, v14
	v_sub_f32_e32 v14, v198, v8
	v_add_f32_e32 v13, v13, v51
	v_exp_f32_e32 v71, v14
	v_sub_f32_e32 v14, v199, v8
	v_add_f32_e32 v13, v13, v53
	v_exp_f32_e32 v75, v14
	v_sub_f32_e32 v14, v200, v8
	v_add_f32_e32 v13, v13, v58
	v_exp_f32_e32 v52, v14
	v_sub_f32_e32 v14, v201, v8
	v_add_f32_e32 v13, v13, v63
	v_exp_f32_e32 v54, v14
	v_sub_f32_e32 v14, v202, v8
	v_add_f32_e32 v13, v13, v71
	v_exp_f32_e32 v65, v14
	v_sub_f32_e32 v14, v203, v8
	v_add_f32_e32 v13, v13, v75
	v_exp_f32_e32 v69, v14
	v_sub_f32_e32 v14, v204, v8
	v_add_f32_e32 v13, v13, v52
	v_exp_f32_e32 v72, v14
	v_sub_f32_e32 v14, v205, v8
	v_add_f32_e32 v13, v13, v54
	v_exp_f32_e32 v77, v14
	v_sub_f32_e32 v14, v206, v8
	v_add_f32_e32 v13, v13, v65
	v_exp_f32_e32 v126, v14
	v_sub_f32_e32 v14, v207, v8
	v_add_f32_e32 v13, v13, v69
	v_exp_f32_e32 v129, v14
	v_sub_f32_e32 v14, v208, v8
	v_add_f32_e32 v13, v13, v72
	v_exp_f32_e32 v67, v14
	v_sub_f32_e32 v14, v125, v8
	v_add_f32_e32 v13, v13, v77
	v_exp_f32_e32 v70, v14
	v_sub_f32_e32 v14, v124, v8
	v_add_f32_e32 v13, v13, v126
	v_exp_f32_e32 v80, v14
	v_sub_f32_e32 v14, v123, v8
	v_add_f32_e32 v13, v13, v129
	v_exp_f32_e32 v124, v14
	v_sub_f32_e32 v14, v122, v8
	v_add_f32_e32 v13, v13, v67
	v_exp_f32_e32 v127, v14
	v_sub_f32_e32 v14, v79, v8
	v_add_f32_e32 v13, v13, v70
	v_exp_f32_e32 v131, v14
	v_sub_f32_e32 v14, v78, v8
	v_add_f32_e32 v13, v13, v80
	v_exp_f32_e32 v199, v14
	v_sub_f32_e32 v14, v76, v8
	v_add_f32_e32 v13, v13, v124
	v_exp_f32_e32 v201, v14
	v_sub_f32_e32 v14, v74, v8
	v_add_f32_e32 v13, v13, v127
	v_exp_f32_e32 v121, v14
	v_sub_f32_e32 v14, v73, v8
	v_add_f32_e32 v13, v13, v131
	v_exp_f32_e32 v125, v14
	v_sub_f32_e32 v14, v68, v8
	v_add_f32_e32 v13, v13, v199
	v_exp_f32_e32 v192, v14
	v_sub_f32_e32 v14, v66, v8
	v_add_f32_e32 v13, v13, v201
	v_exp_f32_e32 v196, v14
	v_sub_f32_e32 v14, v64, v8
	v_add_f32_e32 v13, v13, v121
	v_exp_f32_e32 v200, v14
	v_sub_f32_e32 v14, v62, v8
	v_add_f32_e32 v13, v13, v125
	v_exp_f32_e32 v202, v14
	v_sub_f32_e32 v14, v60, v8
	v_add_f32_e32 v13, v13, v192
	v_exp_f32_e32 v203, v14
	v_sub_f32_e32 v14, v57, v8
	v_add_f32_e32 v13, v13, v196
	v_exp_f32_e32 v204, v14
	v_sub_f32_e32 v14, v59, v8
	v_add_f32_e32 v13, v13, v200
	v_exp_f32_e32 v128, v14
	v_sub_f32_e32 v14, v48, v8
	v_add_f32_e32 v13, v13, v202
	v_exp_f32_e32 v130, v14
	v_sub_f32_e32 v14, v55, v8
	v_add_f32_e32 v13, v13, v203
	v_exp_f32_e32 v191, v14
	v_sub_f32_e32 v14, v45, v8
	v_add_f32_e32 v13, v13, v204
	v_exp_f32_e32 v193, v14
	v_sub_f32_e32 v14, v46, v8
	v_add_f32_e32 v13, v13, v128
	v_exp_f32_e32 v194, v14
	v_sub_f32_e32 v14, v27, v8
	v_add_f32_e32 v13, v13, v130
	v_exp_f32_e32 v195, v14
	v_sub_f32_e32 v14, v28, v8
	v_add_f32_e32 v13, v13, v191
	v_exp_f32_e32 v197, v14
	v_sub_f32_e32 v14, v23, v8
	v_add_f32_e32 v13, v13, v193
	v_exp_f32_e32 v198, v14
	v_sub_f32_e32 v14, v24, v8
	v_add_f32_e32 v13, v13, v194
	v_exp_f32_e32 v73, v14
	v_sub_f32_e32 v14, v29, v8
	v_add_f32_e32 v13, v13, v195
	v_exp_f32_e32 v74, v14
	v_sub_f32_e32 v14, v30, v8
	v_add_f32_e32 v13, v13, v197
	v_exp_f32_e32 v76, v14
	v_sub_f32_e32 v14, v25, v8
	v_add_f32_e32 v13, v13, v198
	v_exp_f32_e32 v78, v14
	v_sub_f32_e32 v14, v26, v8
	v_add_f32_e32 v13, v13, v73
	v_exp_f32_e32 v79, v14
	v_sub_f32_e32 v14, v21, v8
	v_add_f32_e32 v13, v13, v74
	v_exp_f32_e32 v120, v14
	v_sub_f32_e32 v14, v22, v8
	v_add_f32_e32 v13, v13, v76
	v_exp_f32_e32 v122, v14
	v_sub_f32_e32 v14, v19, v8
	v_add_f32_e32 v13, v13, v78
	v_exp_f32_e32 v123, v14
	v_sub_f32_e32 v14, v20, v8
	v_add_f32_e32 v13, v13, v79
	v_exp_f32_e32 v55, v14
	v_sub_f32_e32 v14, v17, v8
	v_add_f32_e32 v13, v13, v120
	v_exp_f32_e32 v57, v14
	v_sub_f32_e32 v14, v18, v8
	v_add_f32_e32 v13, v13, v122
	v_exp_f32_e32 v59, v14
	v_sub_f32_e32 v14, v16, v8
	v_add_f32_e32 v13, v13, v123
	v_exp_f32_e32 v60, v14
	v_sub_f32_e32 v12, v12, v8
	v_add_f32_e32 v13, v13, v55
	v_exp_f32_e32 v62, v12
	v_sub_f32_e32 v10, v10, v8
	v_add_f32_e32 v13, v13, v57
	v_exp_f32_e32 v64, v10
	v_sub_f32_e32 v11, v11, v8
	v_add_f32_e32 v13, v13, v59
	v_exp_f32_e32 v66, v11
	v_sub_f32_e32 v9, v9, v8
	v_add_f32_e32 v13, v13, v60
	v_exp_f32_e32 v68, v9
	v_add_f32_e32 v12, v13, v62
	v_add_f32_e32 v10, v12, v64
	v_add_f32_e32 v10, v10, v66
	v_fma_f32 v8, v188, s80, -v8
	v_add_f32_e32 v45, v10, v68
	v_exp_f32_e32 v48, v8
	v_cvt_pk_bf16_f32 v0, v0, v1
	v_cvt_pk_bf16_f32 v1, v2, v3
	v_cvt_pk_bf16_f32 v2, v4, v5
	v_cvt_pk_bf16_f32 v3, v6, v7
	ds_read_b128 v[4:7], v181 offset:36864
	ds_read_b128 v[8:11], v181 offset:53760
	s_waitcnt lgkmcnt(1)
	v_mfma_f32_32x32x16_bf16 v[16:31], v[4:7], v[0:3], 0
	v_cvt_pk_bf16_f32 v220, v32, v33
	v_cvt_pk_bf16_f32 v221, v34, v36
	v_cvt_pk_bf16_f32 v222, v38, v39
	v_cvt_pk_bf16_f32 v223, v44, v49
	ds_read_b128 v[224:227], v181 offset:36896
	ds_read_b128 v[228:231], v181 offset:53792
	v_cvt_pk_bf16_f32 v32, v35, v37
	v_cvt_pk_bf16_f32 v33, v40, v42
	s_waitcnt lgkmcnt(2)
	v_mfma_f32_32x32x16_bf16 v[0:15], v[8:11], v[0:3], 0
	v_cvt_pk_bf16_f32 v34, v47, v50
	v_cvt_pk_bf16_f32 v35, v56, v61
	ds_bpermute_b32 v46, v189, v45
	s_waitcnt lgkmcnt(2)
	v_mfma_f32_32x32x16_bf16 v[16:31], v[224:227], v[220:223], v[16:31]
	s_waitcnt lgkmcnt(1)
	v_mfma_f32_32x32x16_bf16 v[0:15], v[228:231], v[220:223], v[0:15]
	ds_read_b128 v[36:39], v182 offset:36864
	ds_read_b128 v[220:223], v182 offset:53760
	s_waitcnt lgkmcnt(1)
	v_mfma_f32_32x32x16_bf16 v[16:31], v[36:39], v[32:35], v[16:31]
	s_waitcnt lgkmcnt(0)
	v_mfma_f32_32x32x16_bf16 v[0:15], v[220:223], v[32:35], v[0:15]
	v_cvt_pk_bf16_f32 v32, v41, v43
	v_cvt_pk_bf16_f32 v33, v51, v53
	v_cvt_pk_bf16_f32 v34, v58, v63
	v_cvt_pk_bf16_f32 v35, v71, v75
	ds_read_b128 v[36:39], v182 offset:36896
	ds_read_b128 v[40:43], v182 offset:53792
	s_waitcnt lgkmcnt(1)
	v_mfma_f32_32x32x16_bf16 v[16:31], v[36:39], v[32:35], v[16:31]
	s_waitcnt lgkmcnt(0)
	v_mfma_f32_32x32x16_bf16 v[0:15], v[40:43], v[32:35], v[0:15]
	v_cvt_pk_bf16_f32 v32, v52, v54
	v_cvt_pk_bf16_f32 v33, v65, v69
	v_cvt_pk_bf16_f32 v34, v72, v77
	v_cvt_pk_bf16_f32 v35, v126, v129
	ds_read_b128 v[36:39], v183 offset:36864
	ds_read_b128 v[40:43], v183 offset:53760
	s_waitcnt lgkmcnt(1)
	v_mfma_f32_32x32x16_bf16 v[16:31], v[36:39], v[32:35], v[16:31]
	s_waitcnt lgkmcnt(0)
	v_mfma_f32_32x32x16_bf16 v[0:15], v[40:43], v[32:35], v[0:15]
	v_cvt_pk_bf16_f32 v32, v67, v70
	v_cvt_pk_bf16_f32 v33, v80, v124
	v_cvt_pk_bf16_f32 v34, v127, v131
	v_cvt_pk_bf16_f32 v35, v199, v201
	ds_read_b128 v[36:39], v183 offset:36896
	ds_read_b128 v[40:43], v183 offset:53792
	s_waitcnt lgkmcnt(1)
	v_mfma_f32_32x32x16_bf16 v[16:31], v[36:39], v[32:35], v[16:31]
	s_waitcnt lgkmcnt(0)
	v_mfma_f32_32x32x16_bf16 v[0:15], v[40:43], v[32:35], v[0:15]
	v_cvt_pk_bf16_f32 v32, v121, v125
	v_cvt_pk_bf16_f32 v33, v192, v196
	v_cvt_pk_bf16_f32 v34, v200, v202
	v_cvt_pk_bf16_f32 v35, v203, v204
	ds_read_b128 v[36:39], v184 offset:36864
	ds_read_b128 v[40:43], v184 offset:53760
	s_waitcnt lgkmcnt(1)
	v_mfma_f32_32x32x16_bf16 v[16:31], v[36:39], v[32:35], v[16:31]
	s_waitcnt lgkmcnt(0)
	v_mfma_f32_32x32x16_bf16 v[0:15], v[40:43], v[32:35], v[0:15]
	v_cvt_pk_bf16_f32 v32, v128, v130
	v_cvt_pk_bf16_f32 v33, v191, v193
	v_cvt_pk_bf16_f32 v34, v194, v195
	v_cvt_pk_bf16_f32 v35, v197, v198
	ds_read_b128 v[36:39], v184 offset:36896
	ds_read_b128 v[40:43], v184 offset:53792
	s_waitcnt lgkmcnt(1)
	v_mfma_f32_32x32x16_bf16 v[16:31], v[36:39], v[32:35], v[16:31]
	s_waitcnt lgkmcnt(0)
	v_mfma_f32_32x32x16_bf16 v[0:15], v[40:43], v[32:35], v[0:15]
	v_cvt_pk_bf16_f32 v32, v73, v74
	v_cvt_pk_bf16_f32 v33, v76, v78
	v_cvt_pk_bf16_f32 v34, v79, v120
	v_cvt_pk_bf16_f32 v35, v122, v123
	ds_read_b128 v[36:39], v185 offset:36864
	ds_read_b128 v[40:43], v185 offset:53760
	s_waitcnt lgkmcnt(1)
	v_mfma_f32_32x32x16_bf16 v[16:31], v[36:39], v[32:35], v[16:31]
	s_waitcnt lgkmcnt(0)
	v_mfma_f32_32x32x16_bf16 v[0:15], v[40:43], v[32:35], v[0:15]
	v_cvt_pk_bf16_f32 v32, v55, v57
	v_cvt_pk_bf16_f32 v33, v59, v60
	v_cvt_pk_bf16_f32 v34, v62, v64
	v_cvt_pk_bf16_f32 v35, v66, v68
	ds_read_b128 v[36:39], v185 offset:36896
	ds_read_b128 v[40:43], v185 offset:53792
	s_waitcnt lgkmcnt(1)
	v_mfma_f32_32x32x16_bf16 v[16:31], v[36:39], v[32:35], v[16:31]
	s_waitcnt lgkmcnt(0)
	v_mfma_f32_32x32x16_bf16 v[0:15], v[40:43], v[32:35], v[0:15]
	v_add_f32_e32 v32, v45, v46
	v_add_f32_e32 v32, v48, v32
	v_div_scale_f32 v33, s[80:81], v32, v32, 1.0
	v_rcp_f32_e32 v34, v33
	v_readlane_b32 s80, v253, 57
	v_readlane_b32 s81, v253, 58
	v_fma_f32 v35, -v33, v34, 1.0
	v_fmac_f32_e32 v34, v35, v34
	v_div_scale_f32 v35, vcc, 1.0, v32, 1.0
	v_mul_f32_e32 v36, v35, v34
	v_fma_f32 v37, -v33, v36, v35
	v_fmac_f32_e32 v36, v37, v34
	v_fma_f32 v33, -v33, v36, v35
	v_div_fmas_f32 v33, v33, v34, v36
	v_div_fixup_f32 v34, v33, v32, 1.0
	v_lshrrev_b64 v[32:33], 2, v[162:163]
	v_and_b32_e32 v33, 0x3ffff, v33
	v_and_b32_e32 v32, 0xffffffe0, v32
	v_lshlrev_b32_e32 v35, 6, v162
	v_lshlrev_b32_e32 v37, 2, v162
	v_lshl_add_u64 v[32:33], v[32:33], 0, s[34:35]
	v_and_b32_e32 v35, 0x3c0, v35
	v_lshlrev_b32_e32 v36, 7, v162
	v_and_b32_e32 v37, 32, v37
	v_and_b32_e32 v36, 0x3800, v36
	v_lshlrev_b64 v[32:33], 14, v[32:33]
	v_mul_f32_e32 v16, v34, v16
	v_mul_f32_e32 v17, v34, v17
	v_or3_b32 v39, v137, v35, v37
	v_lshl_add_u64 v[32:33], s[80:81], 0, v[32:33]
	v_cvt_pk_bf16_f32 v16, v16, v17
	v_mul_f32_e32 v17, v34, v18
	v_mul_f32_e32 v18, v34, v19
	v_or_b32_e32 v80, v39, v36
	v_or_b32_e32 v38, 0x400, v36
	v_cvt_pk_bf16_f32 v17, v17, v18
	v_lshl_add_u64 v[18:19], v[32:33], 0, v[80:81]
	v_mul_f32_e32 v0, v34, v0
	v_mul_f32_e32 v1, v34, v1
	global_store_dwordx2 v[18:19], v[16:17], off
	v_cvt_pk_bf16_f32 v0, v0, v1
	v_mul_f32_e32 v1, v34, v2
	v_mul_f32_e32 v2, v34, v3
	v_or_b32_e32 v80, v39, v38
	v_cvt_pk_bf16_f32 v1, v1, v2
	v_lshl_add_u64 v[2:3], v[32:33], 0, v[80:81]
	global_store_dwordx2 v[2:3], v[0:1], off
	v_mul_f32_e32 v0, v34, v20
	v_mul_f32_e32 v1, v34, v21
	v_or3_b32 v16, v165, v35, v37
	v_cvt_pk_bf16_f32 v0, v0, v1
	v_mul_f32_e32 v1, v34, v22
	v_mul_f32_e32 v2, v34, v23
	v_or_b32_e32 v80, v16, v36
	v_cvt_pk_bf16_f32 v1, v1, v2
	v_lshl_add_u64 v[2:3], v[32:33], 0, v[80:81]
	global_store_dwordx2 v[2:3], v[0:1], off
	v_mul_f32_e32 v0, v34, v4
	v_mul_f32_e32 v1, v34, v5
	v_cvt_pk_bf16_f32 v0, v0, v1
	v_mul_f32_e32 v1, v34, v6
	v_mul_f32_e32 v2, v34, v7
	v_or_b32_e32 v80, v16, v38
	v_cvt_pk_bf16_f32 v1, v1, v2
	v_lshl_add_u64 v[2:3], v[32:33], 0, v[80:81]
	global_store_dwordx2 v[2:3], v[0:1], off
	v_mul_f32_e32 v0, v34, v24
	v_mul_f32_e32 v1, v34, v25
	v_bitop3_b32 v4, v166, v37, v35 bitop3:0x36
	v_cvt_pk_bf16_f32 v0, v0, v1
	v_mul_f32_e32 v1, v34, v26
	v_mul_f32_e32 v2, v34, v27
	v_or_b32_e32 v80, v4, v36
	v_cvt_pk_bf16_f32 v1, v1, v2
	v_lshl_add_u64 v[2:3], v[32:33], 0, v[80:81]
	global_store_dwordx2 v[2:3], v[0:1], off
	v_mul_f32_e32 v0, v34, v8
	v_mul_f32_e32 v1, v34, v9
	v_cvt_pk_bf16_f32 v0, v0, v1
	v_mul_f32_e32 v1, v34, v10
	v_mul_f32_e32 v2, v34, v11
	v_or_b32_e32 v80, v4, v38
	v_cvt_pk_bf16_f32 v1, v1, v2
	v_lshl_add_u64 v[2:3], v[32:33], 0, v[80:81]
	global_store_dwordx2 v[2:3], v[0:1], off
	v_mul_f32_e32 v0, v34, v28
	v_mul_f32_e32 v1, v34, v29
	v_bitop3_b32 v4, v167, v37, v35 bitop3:0x36
	v_cvt_pk_bf16_f32 v0, v0, v1
	v_mul_f32_e32 v1, v34, v30
	v_mul_f32_e32 v2, v34, v31
	v_or_b32_e32 v80, v4, v36
	v_cvt_pk_bf16_f32 v1, v1, v2
	v_lshl_add_u64 v[2:3], v[32:33], 0, v[80:81]
	global_store_dwordx2 v[2:3], v[0:1], off
	v_mul_f32_e32 v0, v34, v12
	v_mul_f32_e32 v1, v34, v13
	v_cvt_pk_bf16_f32 v0, v0, v1
	v_mul_f32_e32 v1, v34, v14
	v_mul_f32_e32 v2, v34, v15
	v_or_b32_e32 v80, v4, v38
	v_cvt_pk_bf16_f32 v1, v1, v2
	v_lshl_add_u64 v[2:3], v[32:33], 0, v[80:81]
	global_store_dwordx2 v[2:3], v[0:1], off
	ds_read_b128 v[0:3], v177
	ds_read_b128 v[4:7], v177 offset:32
	s_waitcnt lgkmcnt(1)
	v_mfma_f32_32x32x16_bf16 v[64:79], v[0:3], v[116:119], 0
	ds_read_b128 v[0:3], v177 offset:64
	s_waitcnt lgkmcnt(1)
	v_mfma_f32_32x32x16_bf16 v[64:79], v[4:7], v[112:115], v[64:79]
	s_waitcnt lgkmcnt(0)
	v_mfma_f32_32x32x16_bf16 v[64:79], v[0:3], v[108:111], v[64:79]
	ds_read_b128 v[0:3], v177 offset:96
	s_waitcnt lgkmcnt(0)
	v_mfma_f32_32x32x16_bf16 v[64:79], v[0:3], v[104:107], v[64:79]
	ds_read_b128 v[0:3], v178
	ds_read_b128 v[4:7], v178 offset:32
	s_waitcnt lgkmcnt(1)
	v_mfma_f32_32x32x16_bf16 v[48:63], v[0:3], v[116:119], 0
	ds_read_b128 v[0:3], v178 offset:64
	s_nop 6
	v_mul_f32_e32 v66, 0x3e38aa3b, v66
	v_mul_f32_e32 v64, 0x3e38aa3b, v64
	v_mul_f32_e32 v65, 0x3e38aa3b, v65
	v_cndmask_b32_e64 v64, v239, v64, s[82:83]
	v_cndmask_b32_e64 v80, v239, v65, s[84:85]
	v_max3_f32 v65, v190, v64, v80
	s_waitcnt lgkmcnt(1)
	v_mfma_f32_32x32x16_bf16 v[48:63], v[4:7], v[112:115], v[48:63]
	s_waitcnt lgkmcnt(0)
	v_mfma_f32_32x32x16_bf16 v[48:63], v[0:3], v[108:111], v[48:63]
	ds_read_b128 v[0:3], v178 offset:96
	s_waitcnt lgkmcnt(0)
	v_mfma_f32_32x32x16_bf16 v[48:63], v[0:3], v[104:107], v[48:63]
	ds_read_b128 v[0:3], v179
	ds_read_b128 v[4:7], v179 offset:32
	s_waitcnt lgkmcnt(1)
	v_mfma_f32_32x32x16_bf16 v[32:47], v[0:3], v[116:119], 0
	ds_read_b128 v[0:3], v179 offset:64
	s_nop 6
	v_mul_f32_e32 v48, 0x3e38aa3b, v48
	s_waitcnt lgkmcnt(1)
	v_mfma_f32_32x32x16_bf16 v[32:47], v[4:7], v[112:115], v[32:47]
	s_waitcnt lgkmcnt(0)
	v_mfma_f32_32x32x16_bf16 v[32:47], v[0:3], v[108:111], v[32:47]
	ds_read_b128 v[0:3], v179 offset:96
	s_waitcnt lgkmcnt(0)
	v_mfma_f32_32x32x16_bf16 v[32:47], v[0:3], v[104:107], v[32:47]
	ds_read_b128 v[0:3], v180
	ds_read_b128 v[16:19], v180 offset:32
	s_waitcnt lgkmcnt(1)
	v_mfma_f32_32x32x16_bf16 v[0:15], v[0:3], v[116:119], 0
	s_nop 7
	v_mul_f32_e32 v32, 0x3e38aa3b, v32
	s_waitcnt lgkmcnt(0)
	v_mfma_f32_32x32x16_bf16 v[0:15], v[16:19], v[112:115], v[0:15]
	ds_read_b128 v[16:19], v180 offset:64
	s_waitcnt lgkmcnt(0)
	v_mfma_f32_32x32x16_bf16 v[0:15], v[16:19], v[108:111], v[0:15]
	ds_read_b128 v[16:19], v180 offset:96
	s_waitcnt lgkmcnt(0)
	v_mfma_f32_32x32x16_bf16 v[0:15], v[16:19], v[104:107], v[0:15]
	ds_read_b128 v[16:19], v186
	ds_read_b128 v[120:123], v186 offset:32
	s_waitcnt lgkmcnt(1)
	v_mfma_f32_32x32x16_bf16 v[16:31], v[16:19], v[116:119], 0
	s_waitcnt lgkmcnt(0)
	v_mfma_f32_32x32x16_bf16 v[16:31], v[120:123], v[112:115], v[16:31]
	ds_read_b128 v[112:115], v186 offset:64
	v_cndmask_b32_e64 v122, v239, v32, s[16:17]
	v_mul_f32_e32 v32, 0x3e38aa3b, v33
	v_mul_f32_e32 v33, 0x3e38aa3b, v34
	v_cndmask_b32_e64 v124, v239, v33, s[16:17]
	v_mul_f32_e32 v33, 0x3e38aa3b, v35
	v_cndmask_b32_e64 v125, v239, v33, s[16:17]
	s_waitcnt lgkmcnt(0)
	v_mfma_f32_32x32x16_bf16 v[16:31], v[112:115], v[108:111], v[16:31]
	ds_read_b128 v[108:111], v186 offset:96
	v_cndmask_b32_e64 v112, v239, v48, s[16:17]
	v_mul_f32_e32 v48, 0x3e38aa3b, v49
	v_mul_f32_e32 v49, 0x3e38aa3b, v50
	v_cndmask_b32_e64 v50, v239, v49, s[16:17]
	v_mul_f32_e32 v49, 0x3e38aa3b, v51
	v_cndmask_b32_e64 v51, v239, v49, s[16:17]
	s_waitcnt lgkmcnt(0)
	v_mfma_f32_32x32x16_bf16 v[16:31], v[108:111], v[104:107], v[16:31]
	v_cndmask_b32_e64 v104, v239, v66, s[86:87]
	v_mul_f32_e32 v66, 0x3e38aa3b, v67
	v_cndmask_b32_e64 v105, v239, v66, s[88:89]
	v_mul_f32_e32 v66, 0x3e38aa3b, v68
	v_cndmask_b32_e64 v106, v239, v66, s[90:91]
	v_mul_f32_e32 v66, 0x3e38aa3b, v69
	v_cndmask_b32_e64 v69, v239, v66, s[92:93]
	v_mul_f32_e32 v66, 0x3e38aa3b, v70
	v_cndmask_b32_e64 v107, v239, v66, s[94:95]
	v_mul_f32_e32 v66, 0x3e38aa3b, v71
	v_cndmask_b32_e64 v71, v239, v66, s[96:97]
	v_mul_f32_e32 v66, 0x3e38aa3b, v72
	v_cndmask_b32_e64 v72, v239, v66, s[28:29]
	v_mul_f32_e32 v66, 0x3e38aa3b, v73
	v_cndmask_b32_e64 v108, v239, v66, s[4:5]
	v_mul_f32_e32 v66, 0x3e38aa3b, v74
	v_max3_f32 v65, v65, v104, v105
	v_cndmask_b32_e64 v74, v239, v66, s[6:7]
	v_mul_f32_e32 v66, 0x3e38aa3b, v75
	v_max3_f32 v65, v65, v106, v69
	v_cndmask_b32_e64 v109, v239, v66, s[8:9]
	v_mul_f32_e32 v66, 0x3e38aa3b, v76
	v_mul_f32_e32 v49, 0x3e38aa3b, v52
	v_max3_f32 v65, v65, v107, v71
	v_cndmask_b32_e64 v110, v239, v66, s[10:11]
	v_mul_f32_e32 v66, 0x3e38aa3b, v77
	v_cndmask_b32_e64 v52, v239, v49, s[16:17]
	v_mul_f32_e32 v49, 0x3e38aa3b, v53
	v_max3_f32 v65, v65, v72, v108
	v_cndmask_b32_e64 v77, v239, v66, s[12:13]
	v_mul_f32_e32 v66, 0x3e38aa3b, v78
	v_cndmask_b32_e64 v53, v239, v49, s[16:17]
	v_mul_f32_e32 v49, 0x3e38aa3b, v54
	v_max3_f32 v65, v65, v74, v109
	v_cndmask_b32_e64 v111, v239, v66, s[14:15]
	v_mul_f32_e32 v66, 0x3e38aa3b, v79
	v_cndmask_b32_e64 v54, v239, v49, s[16:17]
	v_mul_f32_e32 v49, 0x3e38aa3b, v55
	v_max3_f32 v65, v65, v110, v77
	v_cndmask_b32_e64 v79, v239, v66, s[18:19]
	v_cndmask_b32_e64 v114, v239, v49, s[16:17]
	v_mul_f32_e32 v49, 0x3e38aa3b, v56
	v_max3_f32 v65, v65, v111, v79
	v_cndmask_b32_e64 v113, v239, v48, s[16:17]
	v_cndmask_b32_e64 v115, v239, v49, s[16:17]
	v_mul_f32_e32 v49, 0x3e38aa3b, v57
	v_max3_f32 v48, v65, v112, v113
	v_cndmask_b32_e64 v57, v239, v49, s[16:17]
	v_mul_f32_e32 v49, 0x3e38aa3b, v58
	v_max3_f32 v48, v48, v50, v51
	v_cndmask_b32_e64 v116, v239, v49, s[16:17]
	v_mul_f32_e32 v49, 0x3e38aa3b, v59
	v_max3_f32 v48, v48, v52, v53
	v_cndmask_b32_e64 v117, v239, v49, s[16:17]
	v_mul_f32_e32 v49, 0x3e38aa3b, v60
	v_mul_f32_e32 v33, 0x3e38aa3b, v36
	v_max3_f32 v48, v48, v54, v114
	v_cndmask_b32_e64 v118, v239, v49, s[16:17]
	v_mul_f32_e32 v49, 0x3e38aa3b, v61
	v_cndmask_b32_e64 v126, v239, v33, s[16:17]
	v_mul_f32_e32 v33, 0x3e38aa3b, v37
	v_max3_f32 v48, v48, v115, v57
	v_cndmask_b32_e64 v119, v239, v49, s[16:17]
	v_mul_f32_e32 v49, 0x3e38aa3b, v62
	v_cndmask_b32_e64 v127, v239, v33, s[16:17]
	v_mul_f32_e32 v33, 0x3e38aa3b, v38
	v_max3_f32 v48, v48, v116, v117
	v_cndmask_b32_e64 v120, v239, v49, s[16:17]
	v_mul_f32_e32 v49, 0x3e38aa3b, v63
	v_cndmask_b32_e64 v128, v239, v33, s[16:17]
	v_mul_f32_e32 v33, 0x3e38aa3b, v39
	v_max3_f32 v48, v48, v118, v119
	v_cndmask_b32_e64 v121, v239, v49, s[16:17]
	v_cndmask_b32_e64 v78, v239, v33, s[16:17]
	v_mul_f32_e32 v33, 0x3e38aa3b, v40
	v_max3_f32 v48, v48, v120, v121
	v_cndmask_b32_e64 v123, v239, v32, s[16:17]
	v_cndmask_b32_e64 v67, v239, v33, s[16:17]
	v_mul_f32_e32 v33, 0x3e38aa3b, v41
	v_max3_f32 v32, v48, v122, v123
	v_cndmask_b32_e64 v70, v239, v33, s[16:17]
	v_mul_f32_e32 v33, 0x3e38aa3b, v42
	v_max3_f32 v32, v32, v124, v125
	v_cndmask_b32_e64 v76, v239, v33, s[16:17]
	v_mul_f32_e32 v33, 0x3e38aa3b, v43
	v_max3_f32 v32, v32, v126, v127
	v_cndmask_b32_e64 v75, v239, v33, s[16:17]
	v_mul_f32_e32 v33, 0x3e38aa3b, v44
	v_max3_f32 v32, v32, v128, v78
	v_cndmask_b32_e64 v73, v239, v33, s[16:17]
	v_mul_f32_e32 v33, 0x3e38aa3b, v45
	v_max3_f32 v32, v32, v67, v70
	v_cndmask_b32_e64 v68, v239, v33, s[16:17]
	v_mul_f32_e32 v33, 0x3e38aa3b, v46
	v_max3_f32 v32, v32, v76, v75
	v_cndmask_b32_e64 v66, v239, v33, s[16:17]
	v_mul_f32_e32 v33, 0x3e38aa3b, v47
	v_max3_f32 v32, v32, v73, v68
	v_cndmask_b32_e64 v65, v239, v33, s[16:17]
	v_max3_f32 v32, v32, v66, v65
	v_mul_f32_e32 v33, 0x3e38aa3b, v0
	v_mul_f32_e32 v34, 0x3e38aa3b, v1
	v_mul_f32_e32 v16, 0x3e38aa3b, v16
	v_max3_f32 v32, v32, v33, v34
	v_mul_f32_e32 v33, 0x3e38aa3b, v2
	v_mul_f32_e32 v34, 0x3e38aa3b, v3
	v_cndmask_b32_e64 v46, v16, v239, s[52:53]
	v_mul_f32_e32 v16, 0x3e38aa3b, v17
	v_mul_f32_e32 v17, 0x3e38aa3b, v18
	v_max3_f32 v32, v32, v33, v34
	v_mul_f32_e32 v33, 0x3e38aa3b, v4
	v_mul_f32_e32 v34, 0x3e38aa3b, v5
	v_cndmask_b32_e64 v48, v17, v239, s[48:49]
	v_mul_f32_e32 v17, 0x3e38aa3b, v19
	v_max3_f32 v32, v32, v33, v34
	v_mul_f32_e32 v33, 0x3e38aa3b, v6
	v_mul_f32_e32 v34, 0x3e38aa3b, v7
	v_cndmask_b32_e64 v56, v17, v239, s[56:57]
	v_mul_f32_e32 v17, 0x3e38aa3b, v20
	v_max3_f32 v32, v32, v33, v34
	v_mul_f32_e32 v33, 0x3e38aa3b, v8
	v_mul_f32_e32 v34, 0x3e38aa3b, v9
	v_cndmask_b32_e64 v58, v17, v239, s[38:39]
	v_mul_f32_e32 v17, 0x3e38aa3b, v21
	v_max3_f32 v32, v32, v33, v34
	v_mul_f32_e32 v33, 0x3e38aa3b, v10
	v_mul_f32_e32 v34, 0x3e38aa3b, v11
	v_cndmask_b32_e64 v59, v17, v239, s[2:3]
	v_mul_f32_e32 v17, 0x3e38aa3b, v22
	v_max3_f32 v32, v32, v33, v34
	v_mul_f32_e32 v33, 0x3e38aa3b, v12
	v_mul_f32_e32 v34, 0x3e38aa3b, v13
	v_cndmask_b32_e64 v61, v17, v239, s[40:41]
	v_mul_f32_e32 v17, 0x3e38aa3b, v23
	v_max3_f32 v32, v32, v33, v34
	v_mul_f32_e32 v33, 0x3e38aa3b, v14
	v_mul_f32_e32 v34, 0x3e38aa3b, v15
	v_cndmask_b32_e64 v63, v17, v239, s[42:43]
	v_mul_f32_e32 v17, 0x3e38aa3b, v24
	v_max3_f32 v32, v32, v33, v34
	v_cndmask_b32_e64 v47, v239, v16, s[0:1]
	v_cndmask_b32_e64 v24, v17, v239, s[44:45]
	v_mul_f32_e32 v17, 0x3e38aa3b, v25
	v_max3_f32 v16, v32, v46, v47
	v_cndmask_b32_e64 v25, v17, v239, s[68:69]
	v_mul_f32_e32 v17, 0x3e38aa3b, v26
	v_max3_f32 v16, v16, v48, v56
	v_cndmask_b32_e64 v26, v17, v239, s[70:71]
	v_mul_f32_e32 v17, 0x3e38aa3b, v27
	v_max3_f32 v16, v16, v58, v59
	v_cndmask_b32_e64 v27, v17, v239, s[72:73]
	v_mul_f32_e32 v17, 0x3e38aa3b, v28
	v_max3_f32 v16, v16, v61, v63
	v_cndmask_b32_e64 v28, v17, v239, s[74:75]
	v_mul_f32_e32 v17, 0x3e38aa3b, v29
	v_max3_f32 v16, v16, v24, v25
	v_cndmask_b32_e64 v29, v17, v239, s[76:77]
	v_mul_f32_e32 v17, 0x3e38aa3b, v30
	v_max3_f32 v16, v16, v26, v27
	v_cndmask_b32_e64 v30, v17, v239, s[78:79]
	v_mul_f32_e32 v17, 0x3e38aa3b, v31
	v_max3_f32 v16, v16, v28, v29
	v_cndmask_b32_e64 v31, v17, v239, s[36:37]
	v_max3_f32 v16, v16, v30, v31
	ds_bpermute_b32 v17, v189, v16
	s_mov_b32 s0, 0x3e38aa3b
	s_waitcnt lgkmcnt(0)
	v_max_f32_e32 v17, v17, v17
	v_max_f32_e32 v130, v16, v17
	v_sub_f32_e32 v16, v64, v130
	v_exp_f32_e32 v16, v16
	v_sub_f32_e32 v17, v80, v130
	v_exp_f32_e32 v17, v17
	v_sub_f32_e32 v36, v109, v130
	v_add_f32_e32 v18, 0, v16
	v_exp_f32_e32 v36, v36
	v_add_f32_e32 v19, v18, v17
	v_sub_f32_e32 v18, v104, v130
	v_exp_f32_e32 v18, v18
	v_sub_f32_e32 v37, v110, v130
	v_exp_f32_e32 v38, v37
	v_sub_f32_e32 v37, v77, v130
	v_add_f32_e32 v20, v19, v18
	v_sub_f32_e32 v19, v105, v130
	v_exp_f32_e32 v19, v19
	v_exp_f32_e32 v39, v37
	v_sub_f32_e32 v37, v111, v130
	v_exp_f32_e32 v44, v37
	v_add_f32_e32 v21, v20, v19
	v_sub_f32_e32 v20, v106, v130
	v_exp_f32_e32 v20, v20
	v_sub_f32_e32 v37, v79, v130
	v_exp_f32_e32 v49, v37
	v_sub_f32_e32 v42, v51, v130
	v_add_f32_e32 v22, v21, v20
	v_sub_f32_e32 v21, v69, v130
	v_exp_f32_e32 v21, v21
	v_exp_f32_e32 v42, v42
	v_sub_f32_e32 v43, v52, v130
	v_exp_f32_e32 v45, v43
	v_add_f32_e32 v23, v22, v21
	v_sub_f32_e32 v22, v107, v130
	v_exp_f32_e32 v22, v22
	v_sub_f32_e32 v43, v53, v130
	v_sub_f32_e32 v53, v117, v130
	v_exp_f32_e32 v53, v53
	v_add_f32_e32 v32, v23, v22
	v_sub_f32_e32 v23, v71, v130
	v_exp_f32_e32 v23, v23
	v_sub_f32_e32 v80, v128, v130
	v_exp_f32_e32 v109, v80
	v_sub_f32_e32 v78, v78, v130
	v_add_f32_e32 v33, v32, v23
	v_sub_f32_e32 v32, v72, v130
	v_exp_f32_e32 v32, v32
	v_sub_f32_e32 v67, v67, v130
	v_exp_f32_e32 v67, v67
	v_sub_f32_e32 v70, v70, v130
	v_add_f32_e32 v34, v33, v32
	v_sub_f32_e32 v33, v108, v130
	v_exp_f32_e32 v33, v33
	v_exp_f32_e32 v70, v70
	v_sub_f32_e32 v76, v76, v130
	v_sub_f32_e32 v75, v75, v130
	v_add_f32_e32 v35, v34, v33
	v_sub_f32_e32 v34, v74, v130
	v_exp_f32_e32 v34, v34
	v_exp_f32_e32 v107, v75
	v_sub_f32_e32 v73, v73, v130
	v_exp_f32_e32 v111, v73
	v_add_f32_e32 v35, v35, v34
	v_add_f32_e32 v35, v35, v36
	v_add_f32_e32 v35, v35, v38
	v_add_f32_e32 v35, v35, v39
	v_add_f32_e32 v35, v35, v44
	v_add_f32_e32 v37, v35, v49
	v_sub_f32_e32 v35, v112, v130
	v_exp_f32_e32 v35, v35
	v_exp_f32_e32 v112, v78
	v_sub_f32_e32 v68, v68, v130
	v_sub_f32_e32 v66, v66, v130
	v_add_f32_e32 v40, v37, v35
	v_sub_f32_e32 v37, v113, v130
	v_exp_f32_e32 v37, v37
	v_sub_f32_e32 v65, v65, v130
	v_fma_f32 v0, v0, s0, -v130
	v_exp_f32_e32 v104, v0
	v_add_f32_e32 v41, v40, v37
	v_sub_f32_e32 v40, v50, v130
	v_exp_f32_e32 v40, v40
	v_exp_f32_e32 v50, v43
	v_sub_f32_e32 v43, v54, v130
	v_exp_f32_e32 v55, v43
	v_add_f32_e32 v41, v41, v40
	v_sub_f32_e32 v43, v114, v130
	v_add_f32_e32 v41, v41, v42
	v_exp_f32_e32 v60, v43
	v_add_f32_e32 v41, v41, v45
	v_add_f32_e32 v41, v41, v50
	v_add_f32_e32 v41, v41, v55
	v_add_f32_e32 v43, v41, v60
	v_sub_f32_e32 v41, v115, v130
	v_exp_f32_e32 v41, v41
	v_sub_f32_e32 v54, v118, v130
	v_exp_f32_e32 v114, v68
	v_fma_f32 v1, v1, s0, -v130
	v_add_f32_e32 v51, v43, v41
	v_sub_f32_e32 v43, v57, v130
	v_exp_f32_e32 v43, v43
	v_exp_f32_e32 v57, v54
	v_sub_f32_e32 v54, v119, v130
	v_exp_f32_e32 v62, v54
	v_add_f32_e32 v52, v51, v43
	v_sub_f32_e32 v51, v116, v130
	v_exp_f32_e32 v51, v51
	v_sub_f32_e32 v54, v120, v130
	v_exp_f32_e32 v71, v54
	v_sub_f32_e32 v54, v121, v130
	v_add_f32_e32 v52, v52, v51
	v_add_f32_e32 v52, v52, v53
	v_exp_f32_e32 v74, v54
	v_add_f32_e32 v52, v52, v57
	v_add_f32_e32 v52, v52, v62
	v_add_f32_e32 v52, v52, v71
	v_add_f32_e32 v54, v52, v74
	v_sub_f32_e32 v52, v122, v130
	v_exp_f32_e32 v52, v52
	v_exp_f32_e32 v110, v1
	v_fma_f32 v1, v2, s0, -v130
	v_exp_f32_e32 v117, v1
	v_add_f32_e32 v64, v54, v52
	v_sub_f32_e32 v54, v123, v130
	v_exp_f32_e32 v54, v54
	v_exp_f32_e32 v123, v66
	v_fma_f32 v1, v3, s0, -v130
	v_exp_f32_e32 v121, v1
	v_add_f32_e32 v69, v64, v54
	v_sub_f32_e32 v64, v124, v130
	v_exp_f32_e32 v64, v64
	v_fma_f32 v1, v4, s0, -v130
	v_add_f32_e32 v72, v69, v64
	v_sub_f32_e32 v69, v125, v130
	v_exp_f32_e32 v69, v69
	v_exp_f32_e32 v125, v1
	v_fma_f32 v1, v5, s0, -v130
	v_add_f32_e32 v77, v72, v69
	v_sub_f32_e32 v72, v126, v130
	v_exp_f32_e32 v72, v72
	v_exp_f32_e32 v126, v65
	v_add_f32_e32 v79, v77, v72
	v_sub_f32_e32 v77, v127, v130
	v_exp_f32_e32 v77, v77
	v_exp_f32_e32 v127, v1
	v_fma_f32 v1, v6, s0, -v130
	v_exp_f32_e32 v128, v1
	v_add_f32_e32 v79, v79, v77
	v_add_f32_e32 v79, v79, v109
	v_add_f32_e32 v78, v79, v112
	v_exp_f32_e32 v79, v76
	v_add_f32_e32 v78, v78, v67
	v_add_f32_e32 v78, v78, v70
	v_fma_f32 v1, v7, s0, -v130
	v_add_f32_e32 v76, v78, v79
	v_add_f32_e32 v75, v76, v107
	v_add_f32_e32 v73, v75, v111
	v_add_f32_e32 v68, v73, v114
	v_add_f32_e32 v66, v68, v123
	v_add_f32_e32 v65, v66, v126
	v_add_f32_e32 v0, v65, v104
	v_add_f32_e32 v0, v0, v110
	v_add_f32_e32 v0, v0, v117
	v_add_f32_e32 v0, v0, v121
	v_exp_f32_e32 v129, v1
	v_fma_f32 v1, v8, s0, -v130
	v_add_f32_e32 v0, v0, v125
	v_exp_f32_e32 v113, v1
	v_fma_f32 v1, v9, s0, -v130
	v_add_f32_e32 v0, v0, v127
	v_exp_f32_e32 v115, v1
	v_fma_f32 v1, v10, s0, -v130
	v_add_f32_e32 v0, v0, v128
	v_exp_f32_e32 v116, v1
	v_fma_f32 v1, v11, s0, -v130
	v_add_f32_e32 v0, v0, v129
	v_exp_f32_e32 v118, v1
	v_fma_f32 v1, v12, s0, -v130
	v_add_f32_e32 v0, v0, v113
	v_exp_f32_e32 v119, v1
	v_fma_f32 v1, v13, s0, -v130
	v_add_f32_e32 v0, v0, v115
	v_exp_f32_e32 v120, v1
	v_fma_f32 v1, v14, s0, -v130
	v_add_f32_e32 v0, v0, v116
	v_exp_f32_e32 v122, v1
	v_fma_f32 v1, v15, s0, -v130
	v_add_f32_e32 v0, v0, v118
	v_exp_f32_e32 v124, v1
	v_sub_f32_e32 v1, v46, v130
	v_add_f32_e32 v0, v0, v119
	v_exp_f32_e32 v73, v1
	v_sub_f32_e32 v1, v47, v130
	v_add_f32_e32 v0, v0, v120
	v_exp_f32_e32 v75, v1
	v_sub_f32_e32 v1, v48, v130
	v_add_f32_e32 v0, v0, v122
	v_exp_f32_e32 v76, v1
	v_sub_f32_e32 v1, v56, v130
	v_add_f32_e32 v0, v0, v124
	v_exp_f32_e32 v78, v1
	v_sub_f32_e32 v1, v58, v130
	v_add_f32_e32 v0, v0, v73
	v_exp_f32_e32 v80, v1
	v_sub_f32_e32 v1, v59, v130
	v_add_f32_e32 v0, v0, v75
	v_exp_f32_e32 v105, v1
	v_sub_f32_e32 v1, v61, v130
	v_add_f32_e32 v0, v0, v76
	v_exp_f32_e32 v106, v1
	v_sub_f32_e32 v1, v63, v130
	v_add_f32_e32 v0, v0, v78
	v_exp_f32_e32 v108, v1
	v_sub_f32_e32 v1, v24, v130
	v_add_f32_e32 v0, v0, v80
	v_exp_f32_e32 v56, v1
	v_sub_f32_e32 v1, v25, v130
	v_add_f32_e32 v0, v0, v105
	v_exp_f32_e32 v58, v1
	v_sub_f32_e32 v1, v26, v130
	v_add_f32_e32 v0, v0, v106
	v_exp_f32_e32 v59, v1
	v_sub_f32_e32 v1, v27, v130
	v_add_f32_e32 v0, v0, v108
	v_exp_f32_e32 v61, v1
	v_sub_f32_e32 v1, v28, v130
	v_add_f32_e32 v0, v0, v56
	v_exp_f32_e32 v63, v1
	v_sub_f32_e32 v1, v29, v130
	v_add_f32_e32 v0, v0, v58
	v_exp_f32_e32 v65, v1
	v_sub_f32_e32 v1, v30, v130
	v_add_f32_e32 v0, v0, v59
	v_exp_f32_e32 v66, v1
	v_sub_f32_e32 v1, v31, v130
	v_add_f32_e32 v0, v0, v61
	v_exp_f32_e32 v68, v1
	v_add_f32_e32 v0, v0, v63
	v_add_f32_e32 v0, v0, v65
	v_add_f32_e32 v0, v0, v66
	s_mov_b32 s0, 0x3fb8aa3b
	v_add_f32_e32 v46, v0, v68
	v_fma_f32 v0, v188, s0, -v130
	v_exp_f32_e32 v48, v0
	v_cvt_pk_bf16_f32 v0, v16, v17
	v_cvt_pk_bf16_f32 v1, v18, v19
	v_cvt_pk_bf16_f32 v2, v20, v21
	v_cvt_pk_bf16_f32 v3, v22, v23
	ds_read_b128 v[4:7], v182 offset:36864
	ds_read_b128 v[8:11], v182 offset:53760
	s_waitcnt lgkmcnt(1)
	v_mfma_f32_32x32x16_bf16 v[16:31], v[4:7], v[0:3], 0
	ds_bpermute_b32 v47, v189, v46
	v_cvt_pk_bf16_f32 v188, v32, v33
	v_cvt_pk_bf16_f32 v189, v34, v36
	v_cvt_pk_bf16_f32 v190, v38, v39
	v_cvt_pk_bf16_f32 v191, v44, v49
	ds_read_b128 v[192:195], v182 offset:36896
	ds_read_b128 v[196:199], v182 offset:53792
	v_cvt_pk_bf16_f32 v32, v35, v37
	s_waitcnt lgkmcnt(3)
	v_mfma_f32_32x32x16_bf16 v[0:15], v[8:11], v[0:3], 0
	v_cvt_pk_bf16_f32 v33, v40, v42
	v_cvt_pk_bf16_f32 v34, v45, v50
	v_cvt_pk_bf16_f32 v35, v55, v60
	s_waitcnt lgkmcnt(1)
	v_mfma_f32_32x32x16_bf16 v[16:31], v[192:195], v[188:191], v[16:31]
	s_waitcnt lgkmcnt(0)
	v_mfma_f32_32x32x16_bf16 v[0:15], v[196:199], v[188:191], v[0:15]
	ds_read_b128 v[36:39], v183 offset:36864
	ds_read_b128 v[188:191], v183 offset:53760
	s_waitcnt lgkmcnt(1)
	v_mfma_f32_32x32x16_bf16 v[16:31], v[36:39], v[32:35], v[16:31]
	s_waitcnt lgkmcnt(0)
	v_mfma_f32_32x32x16_bf16 v[0:15], v[188:191], v[32:35], v[0:15]
	v_cvt_pk_bf16_f32 v32, v41, v43
	v_cvt_pk_bf16_f32 v33, v51, v53
	v_cvt_pk_bf16_f32 v34, v57, v62
	v_cvt_pk_bf16_f32 v35, v71, v74
	ds_read_b128 v[36:39], v183 offset:36896
	ds_read_b128 v[40:43], v183 offset:53792
	s_waitcnt lgkmcnt(1)
	v_mfma_f32_32x32x16_bf16 v[16:31], v[36:39], v[32:35], v[16:31]
	s_waitcnt lgkmcnt(0)
	v_mfma_f32_32x32x16_bf16 v[0:15], v[40:43], v[32:35], v[0:15]
	v_cvt_pk_bf16_f32 v32, v52, v54
	v_cvt_pk_bf16_f32 v33, v64, v69
	v_cvt_pk_bf16_f32 v34, v72, v77
	v_cvt_pk_bf16_f32 v35, v109, v112
	ds_read_b128 v[36:39], v184 offset:36864
	ds_read_b128 v[40:43], v184 offset:53760
	s_waitcnt lgkmcnt(1)
	v_mfma_f32_32x32x16_bf16 v[16:31], v[36:39], v[32:35], v[16:31]
	s_waitcnt lgkmcnt(0)
	v_mfma_f32_32x32x16_bf16 v[0:15], v[40:43], v[32:35], v[0:15]
	v_cvt_pk_bf16_f32 v32, v67, v70
	v_cvt_pk_bf16_f32 v33, v79, v107
	v_cvt_pk_bf16_f32 v34, v111, v114
	v_cvt_pk_bf16_f32 v35, v123, v126
	ds_read_b128 v[36:39], v184 offset:36896
	ds_read_b128 v[40:43], v184 offset:53792
	s_waitcnt lgkmcnt(1)
	v_mfma_f32_32x32x16_bf16 v[16:31], v[36:39], v[32:35], v[16:31]
	s_waitcnt lgkmcnt(0)
	v_mfma_f32_32x32x16_bf16 v[0:15], v[40:43], v[32:35], v[0:15]
	v_cvt_pk_bf16_f32 v32, v104, v110
	v_cvt_pk_bf16_f32 v33, v117, v121
	v_cvt_pk_bf16_f32 v34, v125, v127
	v_cvt_pk_bf16_f32 v35, v128, v129
	ds_read_b128 v[36:39], v185 offset:36864
	ds_read_b128 v[40:43], v185 offset:53760
	s_waitcnt lgkmcnt(1)
	v_mfma_f32_32x32x16_bf16 v[16:31], v[36:39], v[32:35], v[16:31]
	s_waitcnt lgkmcnt(0)
	v_mfma_f32_32x32x16_bf16 v[0:15], v[40:43], v[32:35], v[0:15]
	v_cvt_pk_bf16_f32 v32, v113, v115
	v_cvt_pk_bf16_f32 v33, v116, v118
	v_cvt_pk_bf16_f32 v34, v119, v120
	v_cvt_pk_bf16_f32 v35, v122, v124
	ds_read_b128 v[36:39], v185 offset:36896
	ds_read_b128 v[40:43], v185 offset:53792
	s_waitcnt lgkmcnt(1)
	v_mfma_f32_32x32x16_bf16 v[16:31], v[36:39], v[32:35], v[16:31]
	s_waitcnt lgkmcnt(0)
	v_mfma_f32_32x32x16_bf16 v[0:15], v[40:43], v[32:35], v[0:15]
	v_cvt_pk_bf16_f32 v32, v73, v75
	v_cvt_pk_bf16_f32 v33, v76, v78
	v_cvt_pk_bf16_f32 v34, v80, v105
	v_cvt_pk_bf16_f32 v35, v106, v108
	ds_read_b128 v[36:39], v187 offset:36864
	ds_read_b128 v[40:43], v187 offset:53760
	s_waitcnt lgkmcnt(1)
	v_mfma_f32_32x32x16_bf16 v[16:31], v[36:39], v[32:35], v[16:31]
	s_waitcnt lgkmcnt(0)
	v_mfma_f32_32x32x16_bf16 v[0:15], v[40:43], v[32:35], v[0:15]
	v_cvt_pk_bf16_f32 v32, v56, v58
	v_cvt_pk_bf16_f32 v33, v59, v61
	v_cvt_pk_bf16_f32 v34, v63, v65
	v_cvt_pk_bf16_f32 v35, v66, v68
	ds_read_b128 v[36:39], v187 offset:36896
	ds_read_b128 v[40:43], v187 offset:53792
	s_waitcnt lgkmcnt(1)
	v_mfma_f32_32x32x16_bf16 v[16:31], v[36:39], v[32:35], v[16:31]
	s_waitcnt lgkmcnt(0)
	v_mfma_f32_32x32x16_bf16 v[0:15], v[40:43], v[32:35], v[0:15]
	v_add_f32_e32 v32, v46, v47
	v_add_f32_e32 v32, v48, v32
	v_div_scale_f32 v33, s[0:1], v32, v32, 1.0
	v_rcp_f32_e32 v34, v33
	s_mov_b64 s[0:1], 0
	v_fma_f32 v35, -v33, v34, 1.0
	v_fmac_f32_e32 v34, v35, v34
	v_div_scale_f32 v35, vcc, 1.0, v32, 1.0
	v_mul_f32_e32 v36, v35, v34
	v_fma_f32 v37, -v33, v36, v35
	v_fmac_f32_e32 v36, v37, v34
	v_fma_f32 v33, -v33, v36, v35
	v_div_fmas_f32 v33, v33, v34, v36
	v_div_fixup_f32 v34, v33, v32, 1.0
	v_lshrrev_b64 v[32:33], 2, v[160:161]
	v_and_b32_e32 v33, 0x3ffff, v33
	v_and_b32_e32 v32, 0xffffffe0, v32
	v_lshlrev_b32_e32 v35, 6, v160
	v_lshlrev_b32_e32 v37, 2, v160
	v_lshl_add_u64 v[32:33], v[32:33], 0, s[34:35]
	v_and_b32_e32 v35, 0x3c0, v35
	v_lshlrev_b32_e32 v36, 7, v160
	v_and_b32_e32 v37, 32, v37
	v_and_b32_e32 v36, 0x3800, v36
	v_lshlrev_b64 v[32:33], 14, v[32:33]
	v_mul_f32_e32 v16, v34, v16
	v_mul_f32_e32 v17, v34, v17
	v_or3_b32 v39, v137, v35, v37
	v_lshl_add_u64 v[32:33], s[80:81], 0, v[32:33]
	v_cvt_pk_bf16_f32 v16, v16, v17
	v_mul_f32_e32 v17, v34, v18
	v_mul_f32_e32 v18, v34, v19
	v_or_b32_e32 v80, v39, v36
	v_or_b32_e32 v38, 0x400, v36
	v_cvt_pk_bf16_f32 v17, v17, v18
	v_lshl_add_u64 v[18:19], v[32:33], 0, v[80:81]
	v_mul_f32_e32 v0, v34, v0
	v_mul_f32_e32 v1, v34, v1
	global_store_dwordx2 v[18:19], v[16:17], off
	v_cvt_pk_bf16_f32 v0, v0, v1
	v_mul_f32_e32 v1, v34, v2
	v_mul_f32_e32 v2, v34, v3
	v_or_b32_e32 v80, v39, v38
	v_cvt_pk_bf16_f32 v1, v1, v2
	v_lshl_add_u64 v[2:3], v[32:33], 0, v[80:81]
	global_store_dwordx2 v[2:3], v[0:1], off
	v_mul_f32_e32 v0, v34, v20
	v_mul_f32_e32 v1, v34, v21
	v_or3_b32 v16, v165, v35, v37
	v_cvt_pk_bf16_f32 v0, v0, v1
	v_mul_f32_e32 v1, v34, v22
	v_mul_f32_e32 v2, v34, v23
	v_or_b32_e32 v80, v16, v36
	v_cvt_pk_bf16_f32 v1, v1, v2
	v_lshl_add_u64 v[2:3], v[32:33], 0, v[80:81]
	global_store_dwordx2 v[2:3], v[0:1], off
	v_mul_f32_e32 v0, v34, v4
	v_mul_f32_e32 v1, v34, v5
	v_cvt_pk_bf16_f32 v0, v0, v1
	v_mul_f32_e32 v1, v34, v6
	v_mul_f32_e32 v2, v34, v7
	v_or_b32_e32 v80, v16, v38
	v_cvt_pk_bf16_f32 v1, v1, v2
	v_lshl_add_u64 v[2:3], v[32:33], 0, v[80:81]
	global_store_dwordx2 v[2:3], v[0:1], off
	v_mul_f32_e32 v0, v34, v24
	v_mul_f32_e32 v1, v34, v25
	v_bitop3_b32 v4, v166, v37, v35 bitop3:0x36
	v_cvt_pk_bf16_f32 v0, v0, v1
	v_mul_f32_e32 v1, v34, v26
	v_mul_f32_e32 v2, v34, v27
	v_or_b32_e32 v80, v4, v36
	v_cvt_pk_bf16_f32 v1, v1, v2
	v_lshl_add_u64 v[2:3], v[32:33], 0, v[80:81]
	global_store_dwordx2 v[2:3], v[0:1], off
	v_mul_f32_e32 v0, v34, v8
	v_mul_f32_e32 v1, v34, v9
	v_cvt_pk_bf16_f32 v0, v0, v1
	v_mul_f32_e32 v1, v34, v10
	v_mul_f32_e32 v2, v34, v11
	v_or_b32_e32 v80, v4, v38
	v_cvt_pk_bf16_f32 v1, v1, v2
	v_lshl_add_u64 v[2:3], v[32:33], 0, v[80:81]
	global_store_dwordx2 v[2:3], v[0:1], off
	v_mul_f32_e32 v0, v34, v28
	v_mul_f32_e32 v1, v34, v29
	v_bitop3_b32 v4, v167, v37, v35 bitop3:0x36
	v_cvt_pk_bf16_f32 v0, v0, v1
	v_mul_f32_e32 v1, v34, v30
	v_mul_f32_e32 v2, v34, v31
	v_or_b32_e32 v80, v4, v36
	v_cvt_pk_bf16_f32 v1, v1, v2
	v_lshl_add_u64 v[2:3], v[32:33], 0, v[80:81]
	global_store_dwordx2 v[2:3], v[0:1], off
	v_mul_f32_e32 v0, v34, v12
	v_mul_f32_e32 v1, v34, v13
	v_cvt_pk_bf16_f32 v0, v0, v1
	v_mul_f32_e32 v1, v34, v14
	v_mul_f32_e32 v2, v34, v15
	v_or_b32_e32 v80, v4, v38
	v_cvt_pk_bf16_f32 v1, v1, v2
	v_lshl_add_u64 v[2:3], v[32:33], 0, v[80:81]
	global_store_dwordx2 v[2:3], v[0:1], off

.LBB0_457:
	s_cmpk_gt_i32 s4, 0x1ff
	s_cselect_b64 s[0:1], -1, 0
	s_cmp_gt_u32 s31, 1
	v_readlane_b32 s8, v250, 26
	s_cselect_b64 s[6:7], -1, 0
	v_readlane_b32 s9, v250, 27
	s_and_b64 s[6:7], s[8:9], s[6:7]
	s_or_b64 s[6:7], s[0:1], s[6:7]
	s_mov_b64 s[0:1], -1
	s_and_b64 vcc, exec, s[6:7]
	s_cbranch_vccnz .LBB0_454
	s_ashr_i32 s0, s4, 8
	s_bfe_u32 s7, s4, 0x60002
	s_ashr_i32 s1, s0, 31
	s_and_b32 s6, s4, 3
	s_lshl_b64 s[0:1], s[0:1], 13
	s_lshl_b32 s4, s7, 7
	s_or_b32 s0, s0, s4
	s_lshl_b32 s4, s6, 8
	v_readlane_b32 s5, v252, 24
	s_add_i32 s4, s4, s5
	s_ashr_i32 s5, s4, 31
	v_mov_b32_e32 v163, s1
	v_or_b32_e32 v162, s0, v140
	v_lshl_add_u64 v[4:5], s[4:5], 1, v[134:135]
	v_lshlrev_b64 v[0:1], 11, v[162:163]
	v_lshl_add_u64 v[6:7], v[4:5], 0, v[0:1]
	v_mov_b32_e32 v161, s1
	v_or_b32_e32 v160, s0, v142
	global_load_dwordx4 v[0:3], v[6:7], off
	global_load_dwordx4 v[128:131], v[6:7], off offset:32
	global_load_dwordx4 v[124:127], v[6:7], off offset:64
	global_load_dwordx4 v[120:123], v[6:7], off offset:96
	v_lshlrev_b64 v[6:7], 11, v[160:161]
	v_lshl_add_u64 v[4:5], v[4:5], 0, v[6:7]
	global_load_dwordx4 v[116:119], v[4:5], off
	global_load_dwordx4 v[112:115], v[4:5], off offset:32
	global_load_dwordx4 v[108:111], v[4:5], off offset:64
	global_load_dwordx4 v[104:107], v[4:5], off offset:96
	s_waitcnt lgkmcnt(0)
	s_barrier
	s_cmp_lg_u32 s7, 0
	v_readlane_b32 s4, v254, 29
	s_cselect_b64 s[16:17], -1, 0
	v_readlane_b32 s5, v254, 30
	s_lshl_b32 s7, s6, 6
	s_or_b64 s[8:9], s[16:17], s[4:5]
	v_lshlrev_b32_e32 v80, 1, v136
	v_mov_b32_e32 v12, 0
	v_mov_b32_e32 v13, 0
	v_mov_b32_e32 v14, 0
	v_mov_b32_e32 v15, 0
	s_and_saveexec_b64 s[4:5], s[8:9]
	s_cbranch_execz .LBB0_460
	v_lshl_add_u64 v[6:7], s[0:1], 0, v[144:145]
	v_readlane_b32 s8, v250, 59
	v_lshlrev_b64 v[6:7], 9, v[6:7]
	v_readlane_b32 s9, v250, 60
	s_lshl_b32 s34, s7, 1
	s_nop 0
	v_lshl_add_u64 v[6:7], s[8:9], 0, v[6:7]
	v_lshl_add_u64 v[6:7], v[6:7], 0, s[34:35]
	v_lshl_add_u64 v[6:7], v[6:7], 0, v[80:81]
	v_add_co_u32_e32 v6, vcc, 0xffff0000, v6
	s_nop 1
	v_addc_co_u32_e32 v7, vcc, -1, v7, vcc
	global_load_dwordx4 v[12:15], v[6:7], off
.LBB0_460:
	s_or_b64 exec, exec, s[4:5]
	v_readlane_b32 s4, v254, 31
	v_readlane_b32 s5, v254, 32
	s_nop 0
	s_or_b64 s[8:9], s[16:17], s[4:5]
	v_mov_b32_e32 v16, 0
	v_mov_b32_e32 v17, 0
	v_mov_b32_e32 v18, 0
	v_mov_b32_e32 v19, 0
	s_and_saveexec_b64 s[4:5], s[8:9]
	s_cbranch_execz .LBB0_462
	v_lshl_add_u64 v[6:7], s[0:1], 0, v[146:147]
	v_readlane_b32 s8, v250, 59
	v_lshlrev_b64 v[6:7], 9, v[6:7]
	v_readlane_b32 s9, v250, 60
	s_lshl_b32 s34, s7, 1
	s_nop 0
	v_lshl_add_u64 v[6:7], s[8:9], 0, v[6:7]
	v_lshl_add_u64 v[6:7], v[6:7], 0, s[34:35]
	v_lshl_add_u64 v[6:7], v[6:7], 0, v[80:81]
	v_add_co_u32_e32 v6, vcc, 0xffff0000, v6
	s_nop 1
	v_addc_co_u32_e32 v7, vcc, -1, v7, vcc
	global_load_dwordx4 v[16:19], v[6:7], off
.LBB0_462:
	s_or_b64 exec, exec, s[4:5]
	v_readlane_b32 s4, v254, 33
	v_readlane_b32 s5, v254, 34
	s_nop 0
	s_or_b64 s[8:9], s[16:17], s[4:5]
	v_mov_b32_e32 v20, 0
	v_mov_b32_e32 v21, 0
	v_mov_b32_e32 v22, 0
	v_mov_b32_e32 v23, 0
	s_and_saveexec_b64 s[4:5], s[8:9]
	s_cbranch_execz .LBB0_464
	v_lshl_add_u64 v[4:5], s[0:1], 0, v[148:149]
	v_readlane_b32 s8, v250, 59
	v_lshlrev_b64 v[4:5], 9, v[4:5]
	v_readlane_b32 s9, v250, 60
	s_lshl_b32 s34, s7, 1
	s_nop 0
	v_lshl_add_u64 v[4:5], s[8:9], 0, v[4:5]
	v_lshl_add_u64 v[4:5], v[4:5], 0, s[34:35]
	v_lshl_add_u64 v[4:5], v[4:5], 0, v[80:81]
	v_add_co_u32_e32 v4, vcc, 0xffff0000, v4
	s_nop 1
	v_addc_co_u32_e32 v5, vcc, -1, v5, vcc
	global_load_dwordx4 v[20:23], v[4:5], off
.LBB0_464:
	s_or_b64 exec, exec, s[4:5]
	v_readlane_b32 s4, v254, 35
	v_readlane_b32 s5, v254, 36
	s_nop 0
	s_or_b64 s[8:9], s[16:17], s[4:5]
	v_mov_b32_e32 v24, 0
	v_mov_b32_e32 v25, 0
	v_mov_b32_e32 v26, 0
	v_mov_b32_e32 v27, 0
	s_and_saveexec_b64 s[4:5], s[8:9]
	s_cbranch_execz .LBB0_466
	v_lshl_add_u64 v[6:7], s[0:1], 0, v[150:151]
	v_readlane_b32 s8, v250, 59
	v_lshlrev_b64 v[6:7], 9, v[6:7]
	v_readlane_b32 s9, v250, 60
	s_lshl_b32 s34, s7, 1
	s_nop 0
	v_lshl_add_u64 v[6:7], s[8:9], 0, v[6:7]
	v_lshl_add_u64 v[6:7], v[6:7], 0, s[34:35]
	v_lshl_add_u64 v[6:7], v[6:7], 0, v[80:81]
	v_add_co_u32_e32 v6, vcc, 0xffff0000, v6
	s_nop 1
	v_addc_co_u32_e32 v7, vcc, -1, v7, vcc
	global_load_dwordx4 v[24:27], v[6:7], off
.LBB0_466:
	s_or_b64 exec, exec, s[4:5]
	s_nop 0
	v_lshl_add_u64 v[6:7], s[0:1], 0, v[138:139]
	v_readlane_b32 s0, v250, 61
	v_lshlrev_b64 v[6:7], 9, v[6:7]
	v_readlane_b32 s1, v250, 62
	v_readlane_b32 s4, v254, 27
	s_lshl_b32 s34, s7, 1
	v_lshl_add_u64 v[6:7], s[0:1], 0, v[6:7]
	s_mov_b32 s0, 0xffff0000
	v_readlane_b32 s5, v254, 28
	v_lshl_add_u64 v[6:7], v[6:7], 0, s[34:35]
	s_mov_b32 s1, -1
	s_or_b64 s[4:5], s[16:17], s[4:5]
	v_lshl_add_u64 v[10:11], v[6:7], 0, s[0:1]
	v_mov_b32_e32 v28, 0
	v_mov_b32_e32 v29, 0
	v_mov_b32_e32 v30, 0
	v_mov_b32_e32 v31, 0
	s_and_saveexec_b64 s[0:1], s[4:5]
	s_cbranch_execz .LBB0_468
	v_lshl_add_u64 v[4:5], v[152:153], 1, v[10:11]
	global_load_dwordx4 v[28:31], v[4:5], off
.LBB0_468:
	s_or_b64 exec, exec, s[0:1]
	s_nop 0
	v_mov_b32_e32 v32, 0
	v_mov_b32_e32 v33, 0
	v_mov_b32_e32 v34, 0
	v_mov_b32_e32 v35, 0
	s_and_saveexec_b64 s[0:1], s[4:5]
	s_cbranch_execz .LBB0_470
	v_lshl_add_u64 v[6:7], v[154:155], 1, v[10:11]
	global_load_dwordx4 v[32:35], v[6:7], off
.LBB0_470:
	s_or_b64 exec, exec, s[0:1]
	s_nop 0
	v_mov_b32_e32 v36, 0
	v_mov_b32_e32 v37, 0
	v_mov_b32_e32 v38, 0
	v_mov_b32_e32 v39, 0
	s_and_saveexec_b64 s[0:1], s[4:5]
	s_cbranch_execz .LBB0_472
	v_lshl_add_u64 v[4:5], v[156:157], 1, v[10:11]
	global_load_dwordx4 v[36:39], v[4:5], off
.LBB0_472:
	s_or_b64 exec, exec, s[0:1]
	s_nop 0
	v_mov_b32_e32 v4, 0
	v_mov_b32_e32 v5, 0
	v_mov_b32_e32 v6, 0
	v_mov_b32_e32 v7, 0
	s_and_saveexec_b64 s[0:1], s[4:5]
	s_cbranch_execz .LBB0_453
	v_lshl_add_u64 v[4:5], v[158:159], 1, v[10:11]
	global_load_dwordx4 v[4:7], v[4:5], off
	s_branch .LBB0_453
